# static K-loop priority raise (2 instead of 1) for the workgroup with id bit 8 set
# speedup vs baseline: 1.0044x; 1.0016x over previous
; __device__ __forceinline__ f32x4 mfma16(bf16x8 a, bf16x8 b, f32x4 c) { return __builtin_amdgcn_mfma_f32_16x16x32_bf16(a, b, c, 0, 0, 0); }
; template <class Epi>
; __device__ __forceinline__ void gemm_tile(const bf16_t* __restrict__ A, const bf16_t* __restrict__ Bt, int K, int row0, int col0, const Epi& epi, char* smem,
;                                           bool prefetched, bool nvalid, int nrow0, int ncol0) {
;     ...
;     int offA[4][2], offB[4][2];
; #pragma unroll
;     for (int m = 0; m < 4; ++m)
; #pragma unroll
;         for (int ks = 0; ks < 2; ++ks) { const int cx = ((ks * 4 + fq) ^ ((fr >> 1) & 7)) * 16;
;             offA[m][ks] = (wr * 64 + m * 16 + fr) * 128 + cx;
;             offB[m][ks] = TILE_B + (wc * 64 + (m >> 1) * 32 + 8 * (fr >> 2) + 4 * (m & 1) + (fr & 3)) * 128 + cx; }
;     if (prefetched) {
;         if (Epi::STAGED) asm volatile("s_waitcnt vmcnt(8)" ::: "memory");
;         else asm volatile("s_waitcnt vmcnt(0)" ::: "memory");
;     } else {
;         GLDS_STAGE(0, pA, pB, 0);
;         asm volatile("s_waitcnt vmcnt(0)" ::: "memory");
;     }
;     __syncthreads();
;     const int nk = K >> 6;
;     for (int kt = 0; kt < nk; ++kt) {
;         const int cur = kt & 1;
;         if (kt + 1 < nk) GLDS_STAGE(cur ^ 1, pA, pB, kt + 1);
;         const char* cb = smem + cur * 2 * TILE_B;
; #pragma unroll
;         for (int ks = 0; ks < 2; ++ks) {
;             bf16x8 a[4], b[4];
; #pragma unroll
;             for (int m = 0; m < 4; ++m) a[m] = *(const bf16x8*)(cb + offA[m][ks]);
; #pragma unroll
;             for (int n = 0; n < 4; ++n) b[n] = *(const bf16x8*)(cb + offB[n][ks]);
; #pragma unroll
;             for (int m = 0; m < 4; ++m)
; #pragma unroll
;                 for (int n = 0; n < 4; ++n) acc[m][n] = mfma16(b[n], a[m], acc[m][n]);
;         }
;         asm volatile("s_waitcnt vmcnt(0)" ::: "memory");
;         __syncthreads();
.LBB0_154:
	v_readfirstlane_b32 s98, v64
	v_readfirstlane_b32 s99, v65
	v_readfirstlane_b32 s10, v66
	v_readfirstlane_b32 s100, v72
	v_readfirstlane_b32 s101, v73
	v_readfirstlane_b32 s13, v149
	s_nop 3
	s_sub_u32 s14, s10, s98
	s_and_b32 s98, s98, 0xffffff80
	s_and_b32 s100, s100, 0xffffff80
	s_nop 1
	v_subrev_u32_e32 v254, s98, v64
	v_subrev_u32_e32 v255, s100, v72
	s_add_i32 s12, s13, 0x8000
	s_mov_b32 m0, s12
	s_nop 0
	global_load_lds_dwordx4 v254, s[98:99]
	s_add_i32 m0, s12, 0x1000
	s_add_u32 s10, s98, s14
	s_addc_u32 s11, s99, 0
	global_load_lds_dwordx4 v254, s[10:11]
	s_add_i32 m0, s12, 0x2000
	s_add_u32 s10, s10, s14
	s_addc_u32 s11, s11, 0
	global_load_lds_dwordx4 v254, s[10:11]
	s_add_i32 m0, s12, 0x3000
	s_add_u32 s10, s10, s14
	s_addc_u32 s11, s11, 0
	global_load_lds_dwordx4 v254, s[10:11]
	s_add_u32 s98, s98, 0x80
	s_addc_u32 s99, s99, 0
	ds_read_b128 v[182:185], v139
	ds_read_b128 v[64:67], v142 offset:16384
	ds_read_b128 v[68:71], v142 offset:16896
	ds_read_b128 v[72:75], v142 offset:20480
	ds_read_b128 v[76:79], v142 offset:20992
	ds_read_b128 v[186:189], v139 offset:2048
	ds_read_b128 v[246:249], v139 offset:4096
	ds_read_b128 v[250:253], v139 offset:6144
	v_readlane_b32 s8, v245, 0
	s_nop 3
	s_bitcmp1_b32 s8, 8
	s_cbranch_scc1 .Lgk_y_154
	s_setprio 1
	s_branch .Lgk_g_154
.Lgk_y_154:
	s_setprio 2
.Lgk_g_154:
.Lgk_loop_154:
	s_and_b32 s8, s5, 0x8000
	s_xor_b32 s9, s8, 0x8000
	v_or_b32_e32 v173, s8, v141
	v_add_u32_e32 v190, s8, v140
	s_add_i32 m0, s12, 0x4000
	s_nop 0
	s_waitcnt lgkmcnt(6)
	v_mfma_f32_16x16x32_bf16 v[0:3], v[64:67], v[182:185], v[0:3]
	global_load_lds_dwordx4 v255, s[100:101]
	ds_read_b128 v[80:83], v173 offset:16384
	s_waitcnt lgkmcnt(6)
	v_mfma_f32_16x16x32_bf16 v[4:7], v[68:71], v[182:185], v[4:7]
	ds_read_b128 v[128:131], v173 offset:16896
	s_add_i32 m0, s12, 0x5000
	s_add_u32 s10, s100, s14
	s_addc_u32 s11, s101, 0
	s_waitcnt lgkmcnt(6)
	v_mfma_f32_16x16x32_bf16 v[8:11], v[72:75], v[182:185], v[8:11]
	global_load_lds_dwordx4 v255, s[10:11]
	ds_read_b128 v[174:177], v173 offset:20480
	s_waitcnt lgkmcnt(6)
	v_mfma_f32_16x16x32_bf16 v[12:15], v[76:79], v[182:185], v[12:15]
	ds_read_b128 v[178:181], v173 offset:20992
	ds_read_b128 v[182:185], v190
	s_add_i32 m0, s12, 0x6000
	s_add_u32 s10, s10, s14
	s_addc_u32 s11, s11, 0
	s_waitcnt lgkmcnt(7)
	v_mfma_f32_16x16x32_bf16 v[16:19], v[64:67], v[186:189], v[16:19]
	global_load_lds_dwordx4 v255, s[10:11]
	v_mfma_f32_16x16x32_bf16 v[20:23], v[68:71], v[186:189], v[20:23]
	s_add_i32 m0, s12, 0x7000
	s_add_u32 s10, s10, s14
	s_addc_u32 s11, s11, 0
	v_mfma_f32_16x16x32_bf16 v[24:27], v[72:75], v[186:189], v[24:27]
	global_load_lds_dwordx4 v255, s[10:11]
	s_add_u32 s100, s100, 0x80
	s_addc_u32 s101, s101, 0
	v_mfma_f32_16x16x32_bf16 v[28:31], v[76:79], v[186:189], v[28:31]
	ds_read_b128 v[186:189], v190 offset:2048
	s_waitcnt lgkmcnt(7)
	v_mfma_f32_16x16x32_bf16 v[32:35], v[64:67], v[246:249], v[32:35]
	v_mfma_f32_16x16x32_bf16 v[36:39], v[68:71], v[246:249], v[36:39]
	v_mfma_f32_16x16x32_bf16 v[40:43], v[72:75], v[246:249], v[40:43]
	v_mfma_f32_16x16x32_bf16 v[44:47], v[76:79], v[246:249], v[44:47]
	ds_read_b128 v[246:249], v190 offset:4096
	s_waitcnt lgkmcnt(7)
	v_mfma_f32_16x16x32_bf16 v[48:51], v[64:67], v[250:253], v[48:51]
	v_mfma_f32_16x16x32_bf16 v[52:55], v[68:71], v[250:253], v[52:55]
	v_mfma_f32_16x16x32_bf16 v[56:59], v[72:75], v[250:253], v[56:59]
	v_mfma_f32_16x16x32_bf16 v[60:63], v[76:79], v[250:253], v[60:63]
	ds_read_b128 v[250:253], v190 offset:6144
	s_waitcnt lgkmcnt(3)
	v_mfma_f32_16x16x32_bf16 v[0:3], v[80:83], v[182:185], v[0:3]
	v_mfma_f32_16x16x32_bf16 v[4:7], v[128:131], v[182:185], v[4:7]
	v_mfma_f32_16x16x32_bf16 v[8:11], v[174:177], v[182:185], v[8:11]
	v_mfma_f32_16x16x32_bf16 v[12:15], v[178:181], v[182:185], v[12:15]
	s_waitcnt lgkmcnt(2)
	v_mfma_f32_16x16x32_bf16 v[16:19], v[80:83], v[186:189], v[16:19]
	v_mfma_f32_16x16x32_bf16 v[20:23], v[128:131], v[186:189], v[20:23]
	v_mfma_f32_16x16x32_bf16 v[24:27], v[174:177], v[186:189], v[24:27]
	v_mfma_f32_16x16x32_bf16 v[28:31], v[178:181], v[186:189], v[28:31]
	s_waitcnt vmcnt(0)
	s_waitcnt lgkmcnt(0)
	s_barrier
	s_add_i32 s5, s5, 0x8000
	s_cmp_eq_u32 s5, 0x78000
	s_cbranch_scc1 .Lgk_tail_154
	v_or_b32_e32 v173, s9, v142
	v_add_u32_e32 v190, s9, v139
	s_add_i32 s12, s8, s13
	ds_read_b128 v[182:185], v190
	ds_read_b128 v[64:67], v173 offset:16384
	s_mov_b32 m0, s12
	s_nop 0
	v_mfma_f32_16x16x32_bf16 v[32:35], v[80:83], v[246:249], v[32:35]
	global_load_lds_dwordx4 v254, s[98:99]
	ds_read_b128 v[68:71], v173 offset:16896
	v_mfma_f32_16x16x32_bf16 v[36:39], v[128:131], v[246:249], v[36:39]
	ds_read_b128 v[72:75], v173 offset:20480
	s_add_i32 m0, s12, 0x1000
	s_add_u32 s10, s98, s14
	s_addc_u32 s11, s99, 0
	v_mfma_f32_16x16x32_bf16 v[40:43], v[174:177], v[246:249], v[40:43]
	global_load_lds_dwordx4 v254, s[10:11]
	ds_read_b128 v[76:79], v173 offset:20992
	v_mfma_f32_16x16x32_bf16 v[44:47], v[178:181], v[246:249], v[44:47]
	ds_read_b128 v[186:189], v190 offset:2048
	ds_read_b128 v[246:249], v190 offset:4096
	s_add_i32 m0, s12, 0x2000
	s_add_u32 s10, s10, s14
	s_addc_u32 s11, s11, 0
	v_mfma_f32_16x16x32_bf16 v[48:51], v[80:83], v[250:253], v[48:51]
	global_load_lds_dwordx4 v254, s[10:11]
	v_mfma_f32_16x16x32_bf16 v[52:55], v[128:131], v[250:253], v[52:55]
	s_add_i32 m0, s12, 0x3000
	s_add_u32 s10, s10, s14
	s_addc_u32 s11, s11, 0
	v_mfma_f32_16x16x32_bf16 v[56:59], v[174:177], v[250:253], v[56:59]
	global_load_lds_dwordx4 v254, s[10:11]
	s_add_u32 s98, s98, 0x80
	s_addc_u32 s99, s99, 0
	v_mfma_f32_16x16x32_bf16 v[60:63], v[178:181], v[250:253], v[60:63]
	ds_read_b128 v[250:253], v190 offset:6144
	s_branch .Lgk_loop_154

; template <class Epi>
; __device__ __forceinline__ void gemm_tile(const bf16_t* __restrict__ A, const bf16_t* __restrict__ Bt, int K, int row0, int col0, const Epi& epi, char* smem,
;                                           bool prefetched, bool nvalid, int nrow0, int ncol0) {
;     ...
;     int offA[4][2], offB[4][2];
; #pragma unroll
;     for (int m = 0; m < 4; ++m)
; #pragma unroll
;         for (int ks = 0; ks < 2; ++ks) { const int cx = ((ks * 4 + fq) ^ ((fr >> 1) & 7)) * 16;
;             offA[m][ks] = (wr * 64 + m * 16 + fr) * 128 + cx;
;             offB[m][ks] = TILE_B + (wc * 64 + (m >> 1) * 32 + 8 * (fr >> 2) + 4 * (m & 1) + (fr & 3)) * 128 + cx; }
;     if (prefetched) {
;         if (Epi::STAGED) asm volatile("s_waitcnt vmcnt(8)" ::: "memory");
;         else asm volatile("s_waitcnt vmcnt(0)" ::: "memory");
;     } else {
;         GLDS_STAGE(0, pA, pB, 0);
;         asm volatile("s_waitcnt vmcnt(0)" ::: "memory");
;     }
;     __syncthreads();
;     const int nk = K >> 6;
;     for (int kt = 0; kt < nk; ++kt) {
;         const int cur = kt & 1;
;         if (kt + 1 < nk) GLDS_STAGE(cur ^ 1, pA, pB, kt + 1);
;         const char* cb = smem + cur * 2 * TILE_B;
; #pragma unroll
;         for (int ks = 0; ks < 2; ++ks) {
;             bf16x8 a[4], b[4];
; #pragma unroll
;             for (int m = 0; m < 4; ++m) a[m] = *(const bf16x8*)(cb + offA[m][ks]);
; #pragma unroll
;             for (int n = 0; n < 4; ++n) b[n] = *(const bf16x8*)(cb + offB[n][ks]);
.LBB0_197:
	v_readfirstlane_b32 s98, v106
	v_readfirstlane_b32 s99, v107
	v_readfirstlane_b32 s8, v108
	v_readfirstlane_b32 s100, v120
	v_readfirstlane_b32 s101, v121
	v_readfirstlane_b32 s11, v149
	s_nop 3
	s_sub_u32 s15, s8, s98
	s_and_b32 s98, s98, 0xffffff80
	s_and_b32 s100, s100, 0xffffff80
	s_nop 1
	v_subrev_u32_e32 v254, s98, v106
	v_subrev_u32_e32 v255, s100, v120
	s_add_i32 s10, s11, 0x8000
	s_mov_b32 m0, s10
	s_nop 0
	global_load_lds_dwordx4 v254, s[98:99]
	s_add_i32 m0, s10, 0x1000
	s_add_u32 s8, s98, s15
	s_addc_u32 s9, s99, 0
	global_load_lds_dwordx4 v254, s[8:9]
	s_add_i32 m0, s10, 0x2000
	s_add_u32 s8, s8, s15
	s_addc_u32 s9, s9, 0
	global_load_lds_dwordx4 v254, s[8:9]
	s_add_i32 m0, s10, 0x3000
	s_add_u32 s8, s8, s15
	s_addc_u32 s9, s9, 0
	global_load_lds_dwordx4 v254, s[8:9]
	s_add_u32 s98, s98, 0x80
	s_addc_u32 s99, s99, 0
	ds_read_b128 v[188:191], v117
	ds_read_b128 v[106:109], v130 offset:16384
	ds_read_b128 v[118:121], v130 offset:16896
	ds_read_b128 v[122:125], v130 offset:20480
	ds_read_b128 v[168:171], v130 offset:20992
	ds_read_b128 v[192:195], v117 offset:2048
	ds_read_b128 v[196:199], v117 offset:4096
	ds_read_b128 v[246:249], v117 offset:6144
	v_readlane_b32 s6, v245, 0
	s_nop 3
	s_bitcmp1_b32 s6, 8
	s_cbranch_scc1 .Lgk_y_197
	s_setprio 1
	s_branch .Lgk_g_197

; __device__ __forceinline__ f32x4 mfma16(bf16x8 a, bf16x8 b, f32x4 c) { return __builtin_amdgcn_mfma_f32_16x16x32_bf16(a, b, c, 0, 0, 0); }
; template <class Epi>
; __device__ __forceinline__ void gemm_tile(const bf16_t* __restrict__ A, const bf16_t* __restrict__ Bt, int K, int row0, int col0, const Epi& epi, char* smem,
;                                           bool prefetched, bool nvalid, int nrow0, int ncol0) {
;     ...
;     for (int kt = 0; kt < nk; ++kt) {
;         const int cur = kt & 1;
;         if (kt + 1 < nk) GLDS_STAGE(cur ^ 1, pA, pB, kt + 1);
;         const char* cb = smem + cur * 2 * TILE_B;
; #pragma unroll
;         for (int ks = 0; ks < 2; ++ks) {
;             bf16x8 a[4], b[4];
; #pragma unroll
;             for (int m = 0; m < 4; ++m) a[m] = *(const bf16x8*)(cb + offA[m][ks]);
; #pragma unroll
;             for (int n = 0; n < 4; ++n) b[n] = *(const bf16x8*)(cb + offB[n][ks]);
; #pragma unroll
;             for (int m = 0; m < 4; ++m)
; #pragma unroll
;                 for (int n = 0; n < 4; ++n) acc[m][n] = mfma16(b[n], a[m], acc[m][n]);
;         }
;         asm volatile("s_waitcnt vmcnt(0)" ::: "memory");
;         __syncthreads();
.Lgk_g_197:
.Lgk_loop_197:
	s_and_b32 s6, s1, 0x8000
	s_xor_b32 s7, s6, 0x8000
	v_or_b32_e32 v167, s6, v129
	v_add_u32_e32 v250, s6, v128
	s_add_i32 m0, s10, 0x4000
	s_nop 0
	s_waitcnt lgkmcnt(6)
	v_mfma_f32_16x16x32_bf16 v[0:3], v[106:109], v[188:191], v[0:3]
	global_load_lds_dwordx4 v255, s[100:101]
	ds_read_b128 v[172:175], v167 offset:16384
	s_waitcnt lgkmcnt(6)
	v_mfma_f32_16x16x32_bf16 v[4:7], v[118:121], v[188:191], v[4:7]
	ds_read_b128 v[176:179], v167 offset:16896
	s_add_i32 m0, s10, 0x5000
	s_add_u32 s8, s100, s15
	s_addc_u32 s9, s101, 0
	s_waitcnt lgkmcnt(6)
	v_mfma_f32_16x16x32_bf16 v[8:11], v[122:125], v[188:191], v[8:11]
	global_load_lds_dwordx4 v255, s[8:9]
	ds_read_b128 v[180:183], v167 offset:20480
	s_waitcnt lgkmcnt(6)
	v_mfma_f32_16x16x32_bf16 v[12:15], v[168:171], v[188:191], v[12:15]
	ds_read_b128 v[184:187], v167 offset:20992
	ds_read_b128 v[188:191], v250
	s_add_i32 m0, s10, 0x6000
	s_add_u32 s8, s8, s15
	s_addc_u32 s9, s9, 0
	s_waitcnt lgkmcnt(7)
	v_mfma_f32_16x16x32_bf16 v[16:19], v[106:109], v[192:195], v[16:19]
	global_load_lds_dwordx4 v255, s[8:9]
	v_mfma_f32_16x16x32_bf16 v[20:23], v[118:121], v[192:195], v[20:23]
	s_add_i32 m0, s10, 0x7000
	s_add_u32 s8, s8, s15
	s_addc_u32 s9, s9, 0
	v_mfma_f32_16x16x32_bf16 v[24:27], v[122:125], v[192:195], v[24:27]
	global_load_lds_dwordx4 v255, s[8:9]
	s_add_u32 s100, s100, 0x80
	s_addc_u32 s101, s101, 0
	v_mfma_f32_16x16x32_bf16 v[28:31], v[168:171], v[192:195], v[28:31]
	ds_read_b128 v[192:195], v250 offset:2048
	s_waitcnt lgkmcnt(7)
	v_mfma_f32_16x16x32_bf16 v[32:35], v[106:109], v[196:199], v[32:35]
	v_mfma_f32_16x16x32_bf16 v[36:39], v[118:121], v[196:199], v[36:39]
	v_mfma_f32_16x16x32_bf16 v[40:43], v[122:125], v[196:199], v[40:43]
	v_mfma_f32_16x16x32_bf16 v[44:47], v[168:171], v[196:199], v[44:47]
	ds_read_b128 v[196:199], v250 offset:4096
	s_waitcnt lgkmcnt(7)
	v_mfma_f32_16x16x32_bf16 v[48:51], v[106:109], v[246:249], v[48:51]
	v_mfma_f32_16x16x32_bf16 v[52:55], v[118:121], v[246:249], v[52:55]
	v_mfma_f32_16x16x32_bf16 v[56:59], v[122:125], v[246:249], v[56:59]
	v_mfma_f32_16x16x32_bf16 v[60:63], v[168:171], v[246:249], v[60:63]
	ds_read_b128 v[246:249], v250 offset:6144
	s_waitcnt lgkmcnt(3)
	v_mfma_f32_16x16x32_bf16 v[0:3], v[172:175], v[188:191], v[0:3]
	v_mfma_f32_16x16x32_bf16 v[4:7], v[176:179], v[188:191], v[4:7]
	v_mfma_f32_16x16x32_bf16 v[8:11], v[180:183], v[188:191], v[8:11]
	v_mfma_f32_16x16x32_bf16 v[12:15], v[184:187], v[188:191], v[12:15]
	s_waitcnt lgkmcnt(2)
	v_mfma_f32_16x16x32_bf16 v[16:19], v[172:175], v[192:195], v[16:19]
	v_mfma_f32_16x16x32_bf16 v[20:23], v[176:179], v[192:195], v[20:23]
	v_mfma_f32_16x16x32_bf16 v[24:27], v[180:183], v[192:195], v[24:27]
	v_mfma_f32_16x16x32_bf16 v[28:31], v[184:187], v[192:195], v[28:31]
	s_waitcnt vmcnt(0)
	s_waitcnt lgkmcnt(0)
	s_barrier
	s_add_i32 s1, s1, 0x8000
	s_cmp_eq_u32 s1, 0x78000
	s_cbranch_scc1 .Lgk_tail_197
	v_or_b32_e32 v167, s7, v130
	v_add_u32_e32 v250, s7, v117
	s_add_i32 s10, s6, s11
	ds_read_b128 v[188:191], v250
	ds_read_b128 v[106:109], v167 offset:16384
	s_mov_b32 m0, s10
	s_nop 0
	v_mfma_f32_16x16x32_bf16 v[32:35], v[172:175], v[196:199], v[32:35]
	global_load_lds_dwordx4 v254, s[98:99]
	ds_read_b128 v[118:121], v167 offset:16896
	v_mfma_f32_16x16x32_bf16 v[36:39], v[176:179], v[196:199], v[36:39]
	ds_read_b128 v[122:125], v167 offset:20480
	s_add_i32 m0, s10, 0x1000
	s_add_u32 s8, s98, s15
	s_addc_u32 s9, s99, 0
	v_mfma_f32_16x16x32_bf16 v[40:43], v[180:183], v[196:199], v[40:43]
	global_load_lds_dwordx4 v254, s[8:9]
	ds_read_b128 v[168:171], v167 offset:20992
	v_mfma_f32_16x16x32_bf16 v[44:47], v[184:187], v[196:199], v[44:47]
	ds_read_b128 v[192:195], v250 offset:2048
	ds_read_b128 v[196:199], v250 offset:4096
	s_add_i32 m0, s10, 0x2000
	s_add_u32 s8, s8, s15
	s_addc_u32 s9, s9, 0
	v_mfma_f32_16x16x32_bf16 v[48:51], v[172:175], v[246:249], v[48:51]
	global_load_lds_dwordx4 v254, s[8:9]
	v_mfma_f32_16x16x32_bf16 v[52:55], v[176:179], v[246:249], v[52:55]
	s_add_i32 m0, s10, 0x3000
	s_add_u32 s8, s8, s15
	s_addc_u32 s9, s9, 0
	v_mfma_f32_16x16x32_bf16 v[56:59], v[180:183], v[246:249], v[56:59]
	global_load_lds_dwordx4 v254, s[8:9]
	s_add_u32 s98, s98, 0x80
	s_addc_u32 s99, s99, 0
	v_mfma_f32_16x16x32_bf16 v[60:63], v[184:187], v[246:249], v[60:63]
	ds_read_b128 v[246:249], v250 offset:6144
	s_branch .Lgk_loop_197

; template <class Epi>
; __device__ __forceinline__ void gemm_tile(const bf16_t* __restrict__ A, const bf16_t* __restrict__ Bt, int K, int row0, int col0, const Epi& epi, char* smem,
;                                           bool prefetched, bool nvalid, int nrow0, int ncol0) {
;     ...
;     int offA[4][2], offB[4][2];
; #pragma unroll
;     for (int m = 0; m < 4; ++m)
; #pragma unroll
;         for (int ks = 0; ks < 2; ++ks) { const int cx = ((ks * 4 + fq) ^ ((fr >> 1) & 7)) * 16;
;             offA[m][ks] = (wr * 64 + m * 16 + fr) * 128 + cx;
;             offB[m][ks] = TILE_B + (wc * 64 + (m >> 1) * 32 + 8 * (fr >> 2) + 4 * (m & 1) + (fr & 3)) * 128 + cx; }
;     if (prefetched) {
;         if (Epi::STAGED) asm volatile("s_waitcnt vmcnt(8)" ::: "memory");
;         else asm volatile("s_waitcnt vmcnt(0)" ::: "memory");
;     } else {
;         GLDS_STAGE(0, pA, pB, 0);
;         asm volatile("s_waitcnt vmcnt(0)" ::: "memory");
;     }
;     __syncthreads();
;     const int nk = K >> 6;
;     for (int kt = 0; kt < nk; ++kt) {
;         const int cur = kt & 1;
;         if (kt + 1 < nk) GLDS_STAGE(cur ^ 1, pA, pB, kt + 1);
;         const char* cb = smem + cur * 2 * TILE_B;
; #pragma unroll
;         for (int ks = 0; ks < 2; ++ks) {
;             bf16x8 a[4], b[4];
; #pragma unroll
;             for (int m = 0; m < 4; ++m) a[m] = *(const bf16x8*)(cb + offA[m][ks]);
; #pragma unroll
;             for (int n = 0; n < 4; ++n) b[n] = *(const bf16x8*)(cb + offB[n][ks]);
.LBB0_460:
	v_readfirstlane_b32 s98, v94
	v_readfirstlane_b32 s99, v95
	v_readfirstlane_b32 s8, v96
	v_readfirstlane_b32 s100, v102
	v_readfirstlane_b32 s101, v103
	v_readfirstlane_b32 s12, v149
	s_nop 3
	s_sub_u32 s13, s8, s98
	s_and_b32 s98, s98, 0xffffff80
	s_and_b32 s100, s100, 0xffffff80
	s_nop 1
	v_subrev_u32_e32 v254, s98, v94
	v_subrev_u32_e32 v255, s100, v102
	s_add_i32 s11, s12, 0x8000
	s_mov_b32 m0, s11
	s_nop 0
	global_load_lds_dwordx4 v254, s[98:99]
	s_add_i32 m0, s11, 0x1000
	s_add_u32 s8, s98, s13
	s_addc_u32 s9, s99, 0
	global_load_lds_dwordx4 v254, s[8:9]
	s_add_i32 m0, s11, 0x2000
	s_add_u32 s8, s8, s13
	s_addc_u32 s9, s9, 0
	global_load_lds_dwordx4 v254, s[8:9]
	s_add_i32 m0, s11, 0x3000
	s_add_u32 s8, s8, s13
	s_addc_u32 s9, s9, 0
	global_load_lds_dwordx4 v254, s[8:9]
	s_add_u32 s98, s98, 0x80
	s_addc_u32 s99, s99, 0
	ds_read_b128 v[174:177], v110
	ds_read_b128 v[94:97], v87 offset:16384
	ds_read_b128 v[98:101], v87 offset:16896
	ds_read_b128 v[102:105], v87 offset:20480
	ds_read_b128 v[106:109], v87 offset:20992
	ds_read_b128 v[178:181], v110 offset:2048
	ds_read_b128 v[246:249], v110 offset:4096
	ds_read_b128 v[250:253], v110 offset:6144
	v_readlane_b32 s5, v245, 0
	s_nop 3
	s_bitcmp1_b32 s5, 8
	s_cbranch_scc1 .Lgk_y_460
	s_setprio 1
	s_branch .Lgk_g_460

; __device__ __forceinline__ f32x4 mfma16(bf16x8 a, bf16x8 b, f32x4 c) { return __builtin_amdgcn_mfma_f32_16x16x32_bf16(a, b, c, 0, 0, 0); }
; template <class Epi>
; __device__ __forceinline__ void gemm_tile(const bf16_t* __restrict__ A, const bf16_t* __restrict__ Bt, int K, int row0, int col0, const Epi& epi, char* smem,
;                                           bool prefetched, bool nvalid, int nrow0, int ncol0) {
;     ...
;     for (int kt = 0; kt < nk; ++kt) {
;         const int cur = kt & 1;
;         if (kt + 1 < nk) GLDS_STAGE(cur ^ 1, pA, pB, kt + 1);
;         const char* cb = smem + cur * 2 * TILE_B;
; #pragma unroll
;         for (int ks = 0; ks < 2; ++ks) {
;             bf16x8 a[4], b[4];
; #pragma unroll
;             for (int m = 0; m < 4; ++m) a[m] = *(const bf16x8*)(cb + offA[m][ks]);
; #pragma unroll
;             for (int n = 0; n < 4; ++n) b[n] = *(const bf16x8*)(cb + offB[n][ks]);
; #pragma unroll
;             for (int m = 0; m < 4; ++m)
; #pragma unroll
;                 for (int n = 0; n < 4; ++n) acc[m][n] = mfma16(b[n], a[m], acc[m][n]);
;         }
;         asm volatile("s_waitcnt vmcnt(0)" ::: "memory");
;         __syncthreads();
.Lgk_g_460:
.Lgk_loop_460:
	s_and_b32 s5, s1, 0x8000
	s_xor_b32 s10, s5, 0x8000
	v_or_b32_e32 v130, s5, v118
	v_add_u32_e32 v131, s5, v111
	s_add_i32 m0, s11, 0x4000
	s_nop 0
	s_waitcnt lgkmcnt(6)
	v_mfma_f32_16x16x32_bf16 v[0:3], v[94:97], v[174:177], v[0:3]
	global_load_lds_dwordx4 v255, s[100:101]
	ds_read_b128 v[142:145], v130 offset:16384
	s_waitcnt lgkmcnt(6)
	v_mfma_f32_16x16x32_bf16 v[4:7], v[98:101], v[174:177], v[4:7]
	ds_read_b128 v[162:165], v130 offset:16896
	s_add_i32 m0, s11, 0x5000
	s_add_u32 s8, s100, s13
	s_addc_u32 s9, s101, 0
	s_waitcnt lgkmcnt(6)
	v_mfma_f32_16x16x32_bf16 v[8:11], v[102:105], v[174:177], v[8:11]
	global_load_lds_dwordx4 v255, s[8:9]
	ds_read_b128 v[166:169], v130 offset:20480
	s_waitcnt lgkmcnt(6)
	v_mfma_f32_16x16x32_bf16 v[12:15], v[106:109], v[174:177], v[12:15]
	ds_read_b128 v[170:173], v130 offset:20992
	ds_read_b128 v[174:177], v131
	s_add_i32 m0, s11, 0x6000
	s_add_u32 s8, s8, s13
	s_addc_u32 s9, s9, 0
	s_waitcnt lgkmcnt(7)
	v_mfma_f32_16x16x32_bf16 v[16:19], v[94:97], v[178:181], v[16:19]
	global_load_lds_dwordx4 v255, s[8:9]
	v_mfma_f32_16x16x32_bf16 v[20:23], v[98:101], v[178:181], v[20:23]
	s_add_i32 m0, s11, 0x7000
	s_add_u32 s8, s8, s13
	s_addc_u32 s9, s9, 0
	v_mfma_f32_16x16x32_bf16 v[24:27], v[102:105], v[178:181], v[24:27]
	global_load_lds_dwordx4 v255, s[8:9]
	s_add_u32 s100, s100, 0x80
	s_addc_u32 s101, s101, 0
	v_mfma_f32_16x16x32_bf16 v[28:31], v[106:109], v[178:181], v[28:31]
	ds_read_b128 v[178:181], v131 offset:2048
	s_waitcnt lgkmcnt(7)
	v_mfma_f32_16x16x32_bf16 v[32:35], v[94:97], v[246:249], v[32:35]
	v_mfma_f32_16x16x32_bf16 v[36:39], v[98:101], v[246:249], v[36:39]
	v_mfma_f32_16x16x32_bf16 v[40:43], v[102:105], v[246:249], v[40:43]
	v_mfma_f32_16x16x32_bf16 v[44:47], v[106:109], v[246:249], v[44:47]
	ds_read_b128 v[246:249], v131 offset:4096
	s_waitcnt lgkmcnt(7)
	v_mfma_f32_16x16x32_bf16 v[48:51], v[94:97], v[250:253], v[48:51]
	v_mfma_f32_16x16x32_bf16 v[52:55], v[98:101], v[250:253], v[52:55]
	v_mfma_f32_16x16x32_bf16 v[56:59], v[102:105], v[250:253], v[56:59]
	v_mfma_f32_16x16x32_bf16 v[60:63], v[106:109], v[250:253], v[60:63]
	ds_read_b128 v[250:253], v131 offset:6144
	s_waitcnt lgkmcnt(3)
	v_mfma_f32_16x16x32_bf16 v[0:3], v[142:145], v[174:177], v[0:3]
	v_mfma_f32_16x16x32_bf16 v[4:7], v[162:165], v[174:177], v[4:7]
	v_mfma_f32_16x16x32_bf16 v[8:11], v[166:169], v[174:177], v[8:11]
	v_mfma_f32_16x16x32_bf16 v[12:15], v[170:173], v[174:177], v[12:15]
	s_waitcnt lgkmcnt(2)
	v_mfma_f32_16x16x32_bf16 v[16:19], v[142:145], v[178:181], v[16:19]
	v_mfma_f32_16x16x32_bf16 v[20:23], v[162:165], v[178:181], v[20:23]
	v_mfma_f32_16x16x32_bf16 v[24:27], v[166:169], v[178:181], v[24:27]
	v_mfma_f32_16x16x32_bf16 v[28:31], v[170:173], v[178:181], v[28:31]
	s_waitcnt vmcnt(0)
	s_waitcnt lgkmcnt(0)
	s_barrier
	s_add_i32 s1, s1, 0x8000
	s_cmp_eq_u32 s1, 0x78000
	s_cbranch_scc1 .Lgk_tail_460
	v_or_b32_e32 v130, s10, v87
	v_add_u32_e32 v131, s10, v110
	s_add_i32 s11, s5, s12
	ds_read_b128 v[174:177], v131
	ds_read_b128 v[94:97], v130 offset:16384
	s_mov_b32 m0, s11
	s_nop 0
	v_mfma_f32_16x16x32_bf16 v[32:35], v[142:145], v[246:249], v[32:35]
	global_load_lds_dwordx4 v254, s[98:99]
	ds_read_b128 v[98:101], v130 offset:16896
	v_mfma_f32_16x16x32_bf16 v[36:39], v[162:165], v[246:249], v[36:39]
	ds_read_b128 v[102:105], v130 offset:20480
	s_add_i32 m0, s11, 0x1000
	s_add_u32 s8, s98, s13
	s_addc_u32 s9, s99, 0
	v_mfma_f32_16x16x32_bf16 v[40:43], v[166:169], v[246:249], v[40:43]
	global_load_lds_dwordx4 v254, s[8:9]
	ds_read_b128 v[106:109], v130 offset:20992
	v_mfma_f32_16x16x32_bf16 v[44:47], v[170:173], v[246:249], v[44:47]
	ds_read_b128 v[178:181], v131 offset:2048
	ds_read_b128 v[246:249], v131 offset:4096
	s_add_i32 m0, s11, 0x2000
	s_add_u32 s8, s8, s13
	s_addc_u32 s9, s9, 0
	v_mfma_f32_16x16x32_bf16 v[48:51], v[142:145], v[250:253], v[48:51]
	global_load_lds_dwordx4 v254, s[8:9]
	v_mfma_f32_16x16x32_bf16 v[52:55], v[162:165], v[250:253], v[52:55]
	s_add_i32 m0, s11, 0x3000
	s_add_u32 s8, s8, s13
	s_addc_u32 s9, s9, 0
	v_mfma_f32_16x16x32_bf16 v[56:59], v[166:169], v[250:253], v[56:59]
	global_load_lds_dwordx4 v254, s[8:9]
	s_add_u32 s98, s98, 0x80
	s_addc_u32 s99, s99, 0
	v_mfma_f32_16x16x32_bf16 v[60:63], v[170:173], v[250:253], v[60:63]
	ds_read_b128 v[250:253], v131 offset:6144
	s_branch .Lgk_loop_460

; template <class Epi>
; __device__ __forceinline__ void gemm_tile(const bf16_t* __restrict__ A, const bf16_t* __restrict__ Bt, int K, int row0, int col0, const Epi& epi, char* smem,
;                                           bool prefetched, bool nvalid, int nrow0, int ncol0) {
;     ...
;     int offA[4][2], offB[4][2];
; #pragma unroll
;     for (int m = 0; m < 4; ++m)
; #pragma unroll
;         for (int ks = 0; ks < 2; ++ks) { const int cx = ((ks * 4 + fq) ^ ((fr >> 1) & 7)) * 16;
;             offA[m][ks] = (wr * 64 + m * 16 + fr) * 128 + cx;
;             offB[m][ks] = TILE_B + (wc * 64 + (m >> 1) * 32 + 8 * (fr >> 2) + 4 * (m & 1) + (fr & 3)) * 128 + cx; }
;     if (prefetched) {
;         if (Epi::STAGED) asm volatile("s_waitcnt vmcnt(8)" ::: "memory");
;         else asm volatile("s_waitcnt vmcnt(0)" ::: "memory");
;     } else {
;         GLDS_STAGE(0, pA, pB, 0);
;         asm volatile("s_waitcnt vmcnt(0)" ::: "memory");
;     }
;     __syncthreads();
;     const int nk = K >> 6;
;     for (int kt = 0; kt < nk; ++kt) {
;         const int cur = kt & 1;
;         if (kt + 1 < nk) GLDS_STAGE(cur ^ 1, pA, pB, kt + 1);
;         const char* cb = smem + cur * 2 * TILE_B;
; #pragma unroll
;         for (int ks = 0; ks < 2; ++ks) {
;             bf16x8 a[4], b[4];
; #pragma unroll
;             for (int m = 0; m < 4; ++m) a[m] = *(const bf16x8*)(cb + offA[m][ks]);
; #pragma unroll
;             for (int n = 0; n < 4; ++n) b[n] = *(const bf16x8*)(cb + offB[n][ks]);
.LBB0_563:
	v_readfirstlane_b32 s98, v110
	v_readfirstlane_b32 s99, v111
	v_readfirstlane_b32 s10, v118
	v_readfirstlane_b32 s100, v124
	v_readfirstlane_b32 s101, v125
	v_readfirstlane_b32 s17, v149
	s_nop 3
	s_sub_u32 s18, s10, s98
	s_and_b32 s98, s98, 0xffffff80
	s_and_b32 s100, s100, 0xffffff80
	s_nop 1
	v_subrev_u32_e32 v254, s98, v110
	v_subrev_u32_e32 v255, s100, v124
	s_add_i32 s13, s17, 0x8000
	s_mov_b32 m0, s13
	s_nop 0
	global_load_lds_dwordx4 v254, s[98:99]
	s_add_i32 m0, s13, 0x1000
	s_add_u32 s10, s98, s18
	s_addc_u32 s11, s99, 0
	global_load_lds_dwordx4 v254, s[10:11]
	s_add_i32 m0, s13, 0x2000
	s_add_u32 s10, s10, s18
	s_addc_u32 s11, s11, 0
	global_load_lds_dwordx4 v254, s[10:11]
	s_add_i32 m0, s13, 0x3000
	s_add_u32 s10, s10, s18
	s_addc_u32 s11, s11, 0
	global_load_lds_dwordx4 v254, s[10:11]
	s_add_u32 s98, s98, 0x80
	s_addc_u32 s99, s99, 0
	ds_read_b128 v[192:195], v85
	ds_read_b128 v[118:121], v142 offset:16384
	ds_read_b128 v[122:125], v142 offset:16896
	ds_read_b128 v[126:129], v142 offset:20480
	ds_read_b128 v[172:175], v142 offset:20992
	ds_read_b128 v[196:199], v85 offset:2048
	ds_read_b128 v[246:249], v85 offset:4096
	ds_read_b128 v[250:253], v85 offset:6144
	v_readlane_b32 s9, v245, 0
	s_nop 3
	s_bitcmp1_b32 s9, 8
	s_cbranch_scc1 .Lgk_y_563
	s_setprio 1
	s_branch .Lgk_g_563

; __device__ __forceinline__ f32x4 mfma16(bf16x8 a, bf16x8 b, f32x4 c) { return __builtin_amdgcn_mfma_f32_16x16x32_bf16(a, b, c, 0, 0, 0); }
; template <class Epi>
; __device__ __forceinline__ void gemm_tile(const bf16_t* __restrict__ A, const bf16_t* __restrict__ Bt, int K, int row0, int col0, const Epi& epi, char* smem,
;                                           bool prefetched, bool nvalid, int nrow0, int ncol0) {
;     ...
;     for (int kt = 0; kt < nk; ++kt) {
;         const int cur = kt & 1;
;         if (kt + 1 < nk) GLDS_STAGE(cur ^ 1, pA, pB, kt + 1);
;         const char* cb = smem + cur * 2 * TILE_B;
; #pragma unroll
;         for (int ks = 0; ks < 2; ++ks) {
;             bf16x8 a[4], b[4];
; #pragma unroll
;             for (int m = 0; m < 4; ++m) a[m] = *(const bf16x8*)(cb + offA[m][ks]);
; #pragma unroll
;             for (int n = 0; n < 4; ++n) b[n] = *(const bf16x8*)(cb + offB[n][ks]);
; #pragma unroll
;             for (int m = 0; m < 4; ++m)
; #pragma unroll
;                 for (int n = 0; n < 4; ++n) acc[m][n] = mfma16(b[n], a[m], acc[m][n]);
;         }
;         asm volatile("s_waitcnt vmcnt(0)" ::: "memory");
;         __syncthreads();
.Lgk_g_563:
.Lgk_loop_563:
	s_and_b32 s9, s8, 0x8000
	s_xor_b32 s12, s9, 0x8000
	v_or_b32_e32 v110, s9, v141
	v_add_u32_e32 v111, s9, v87
	s_add_i32 m0, s13, 0x4000
	s_nop 0
	s_waitcnt lgkmcnt(6)
	v_mfma_f32_16x16x32_bf16 v[0:3], v[118:121], v[192:195], v[0:3]
	global_load_lds_dwordx4 v255, s[100:101]
	ds_read_b128 v[176:179], v110 offset:16384
	s_waitcnt lgkmcnt(6)
	v_mfma_f32_16x16x32_bf16 v[4:7], v[122:125], v[192:195], v[4:7]
	ds_read_b128 v[180:183], v110 offset:16896
	s_add_i32 m0, s13, 0x5000
	s_add_u32 s10, s100, s18
	s_addc_u32 s11, s101, 0
	s_waitcnt lgkmcnt(6)
	v_mfma_f32_16x16x32_bf16 v[8:11], v[126:129], v[192:195], v[8:11]
	global_load_lds_dwordx4 v255, s[10:11]
	ds_read_b128 v[184:187], v110 offset:20480
	s_waitcnt lgkmcnt(6)
	v_mfma_f32_16x16x32_bf16 v[12:15], v[172:175], v[192:195], v[12:15]
	ds_read_b128 v[188:191], v110 offset:20992
	ds_read_b128 v[192:195], v111
	s_add_i32 m0, s13, 0x6000
	s_add_u32 s10, s10, s18
	s_addc_u32 s11, s11, 0
	s_waitcnt lgkmcnt(7)
	v_mfma_f32_16x16x32_bf16 v[16:19], v[118:121], v[196:199], v[16:19]
	global_load_lds_dwordx4 v255, s[10:11]
	v_mfma_f32_16x16x32_bf16 v[20:23], v[122:125], v[196:199], v[20:23]
	s_add_i32 m0, s13, 0x7000
	s_add_u32 s10, s10, s18
	s_addc_u32 s11, s11, 0
	v_mfma_f32_16x16x32_bf16 v[24:27], v[126:129], v[196:199], v[24:27]
	global_load_lds_dwordx4 v255, s[10:11]
	s_add_u32 s100, s100, 0x80
	s_addc_u32 s101, s101, 0
	v_mfma_f32_16x16x32_bf16 v[28:31], v[172:175], v[196:199], v[28:31]
	ds_read_b128 v[196:199], v111 offset:2048
	s_waitcnt lgkmcnt(7)
	v_mfma_f32_16x16x32_bf16 v[32:35], v[118:121], v[246:249], v[32:35]
	v_mfma_f32_16x16x32_bf16 v[36:39], v[122:125], v[246:249], v[36:39]
	v_mfma_f32_16x16x32_bf16 v[40:43], v[126:129], v[246:249], v[40:43]
	v_mfma_f32_16x16x32_bf16 v[44:47], v[172:175], v[246:249], v[44:47]
	ds_read_b128 v[246:249], v111 offset:4096
	s_waitcnt lgkmcnt(7)
	v_mfma_f32_16x16x32_bf16 v[48:51], v[118:121], v[250:253], v[48:51]
	v_mfma_f32_16x16x32_bf16 v[52:55], v[122:125], v[250:253], v[52:55]
	v_mfma_f32_16x16x32_bf16 v[56:59], v[126:129], v[250:253], v[56:59]
	v_mfma_f32_16x16x32_bf16 v[60:63], v[172:175], v[250:253], v[60:63]
	ds_read_b128 v[250:253], v111 offset:6144
	s_waitcnt lgkmcnt(3)
	v_mfma_f32_16x16x32_bf16 v[0:3], v[176:179], v[192:195], v[0:3]
	v_mfma_f32_16x16x32_bf16 v[4:7], v[180:183], v[192:195], v[4:7]
	v_mfma_f32_16x16x32_bf16 v[8:11], v[184:187], v[192:195], v[8:11]
	v_mfma_f32_16x16x32_bf16 v[12:15], v[188:191], v[192:195], v[12:15]
	s_waitcnt lgkmcnt(2)
	v_mfma_f32_16x16x32_bf16 v[16:19], v[176:179], v[196:199], v[16:19]
	v_mfma_f32_16x16x32_bf16 v[20:23], v[180:183], v[196:199], v[20:23]
	v_mfma_f32_16x16x32_bf16 v[24:27], v[184:187], v[196:199], v[24:27]
	v_mfma_f32_16x16x32_bf16 v[28:31], v[188:191], v[196:199], v[28:31]
	s_waitcnt vmcnt(0)
	s_waitcnt lgkmcnt(0)
	s_barrier
	s_add_i32 s8, s8, 0x8000
	s_cmp_eq_u32 s8, 0x78000
	s_cbranch_scc1 .Lgk_tail_563
	v_or_b32_e32 v110, s12, v142
	v_add_u32_e32 v111, s12, v85
	s_add_i32 s13, s9, s17
	ds_read_b128 v[192:195], v111
	ds_read_b128 v[118:121], v110 offset:16384
	s_mov_b32 m0, s13
	s_nop 0
	v_mfma_f32_16x16x32_bf16 v[32:35], v[176:179], v[246:249], v[32:35]
	global_load_lds_dwordx4 v254, s[98:99]
	ds_read_b128 v[122:125], v110 offset:16896
	v_mfma_f32_16x16x32_bf16 v[36:39], v[180:183], v[246:249], v[36:39]
	ds_read_b128 v[126:129], v110 offset:20480
	s_add_i32 m0, s13, 0x1000
	s_add_u32 s10, s98, s18
	s_addc_u32 s11, s99, 0
	v_mfma_f32_16x16x32_bf16 v[40:43], v[184:187], v[246:249], v[40:43]
	global_load_lds_dwordx4 v254, s[10:11]
	ds_read_b128 v[172:175], v110 offset:20992
	v_mfma_f32_16x16x32_bf16 v[44:47], v[188:191], v[246:249], v[44:47]
	ds_read_b128 v[196:199], v111 offset:2048
	ds_read_b128 v[246:249], v111 offset:4096
	s_add_i32 m0, s13, 0x2000
	s_add_u32 s10, s10, s18
	s_addc_u32 s11, s11, 0
	v_mfma_f32_16x16x32_bf16 v[48:51], v[176:179], v[250:253], v[48:51]
	global_load_lds_dwordx4 v254, s[10:11]
	v_mfma_f32_16x16x32_bf16 v[52:55], v[180:183], v[250:253], v[52:55]
	s_add_i32 m0, s13, 0x3000
	s_add_u32 s10, s10, s18
	s_addc_u32 s11, s11, 0
	v_mfma_f32_16x16x32_bf16 v[56:59], v[184:187], v[250:253], v[56:59]
	global_load_lds_dwordx4 v254, s[10:11]
	s_add_u32 s98, s98, 0x80
	s_addc_u32 s99, s99, 0
	v_mfma_f32_16x16x32_bf16 v[60:63], v[188:191], v[250:253], v[60:63]
	ds_read_b128 v[250:253], v111 offset:6144
	s_branch .Lgk_loop_563

; template <class Epi>
; __device__ __forceinline__ void gemm_tile(const bf16_t* __restrict__ A, const bf16_t* __restrict__ Bt, int K, int row0, int col0, const Epi& epi, char* smem,
;                                           bool prefetched, bool nvalid, int nrow0, int ncol0) {
;     ...
;     int offA[4][2], offB[4][2];
; #pragma unroll
;     for (int m = 0; m < 4; ++m)
; #pragma unroll
;         for (int ks = 0; ks < 2; ++ks) { const int cx = ((ks * 4 + fq) ^ ((fr >> 1) & 7)) * 16;
;             offA[m][ks] = (wr * 64 + m * 16 + fr) * 128 + cx;
;             offB[m][ks] = TILE_B + (wc * 64 + (m >> 1) * 32 + 8 * (fr >> 2) + 4 * (m & 1) + (fr & 3)) * 128 + cx; }
;     if (prefetched) {
;         if (Epi::STAGED) asm volatile("s_waitcnt vmcnt(8)" ::: "memory");
;         else asm volatile("s_waitcnt vmcnt(0)" ::: "memory");
;     } else {
;         GLDS_STAGE(0, pA, pB, 0);
;         asm volatile("s_waitcnt vmcnt(0)" ::: "memory");
;     }
;     __syncthreads();
;     const int nk = K >> 6;
;     for (int kt = 0; kt < nk; ++kt) {
;         const int cur = kt & 1;
;         if (kt + 1 < nk) GLDS_STAGE(cur ^ 1, pA, pB, kt + 1);
;         const char* cb = smem + cur * 2 * TILE_B;
; #pragma unroll
;         for (int ks = 0; ks < 2; ++ks) {
;             bf16x8 a[4], b[4];
; #pragma unroll
;             for (int m = 0; m < 4; ++m) a[m] = *(const bf16x8*)(cb + offA[m][ks]);
; #pragma unroll
;             for (int n = 0; n < 4; ++n) b[n] = *(const bf16x8*)(cb + offB[n][ks]);
.LBB0_619:
	v_readfirstlane_b32 s98, v92
	v_readfirstlane_b32 s99, v93
	v_readfirstlane_b32 s8, v94
	v_readfirstlane_b32 s100, v100
	v_readfirstlane_b32 s101, v101
	v_readfirstlane_b32 s12, v149
	s_nop 3
	s_sub_u32 s13, s8, s98
	s_and_b32 s98, s98, 0xffffff80
	s_and_b32 s100, s100, 0xffffff80
	s_nop 1
	v_subrev_u32_e32 v254, s98, v92
	v_subrev_u32_e32 v255, s100, v100
	s_add_i32 s11, s12, 0x8000
	s_mov_b32 m0, s11
	s_nop 0
	global_load_lds_dwordx4 v254, s[98:99]
	s_add_i32 m0, s11, 0x1000
	s_add_u32 s8, s98, s13
	s_addc_u32 s9, s99, 0
	global_load_lds_dwordx4 v254, s[8:9]
	s_add_i32 m0, s11, 0x2000
	s_add_u32 s8, s8, s13
	s_addc_u32 s9, s9, 0
	global_load_lds_dwordx4 v254, s[8:9]
	s_add_i32 m0, s11, 0x3000
	s_add_u32 s8, s8, s13
	s_addc_u32 s9, s9, 0
	global_load_lds_dwordx4 v254, s[8:9]
	s_add_u32 s98, s98, 0x80
	s_addc_u32 s99, s99, 0
	ds_read_b128 v[174:177], v108
	ds_read_b128 v[92:95], v110 offset:16384
	ds_read_b128 v[96:99], v110 offset:16896
	ds_read_b128 v[100:103], v110 offset:20480
	ds_read_b128 v[104:107], v110 offset:20992
	ds_read_b128 v[178:181], v108 offset:2048
	ds_read_b128 v[246:249], v108 offset:4096
	ds_read_b128 v[250:253], v108 offset:6144
	v_readlane_b32 s3, v245, 0
	s_nop 3
	s_bitcmp1_b32 s3, 8
	s_cbranch_scc1 .Lgk_y_619
	s_setprio 1
	s_branch .Lgk_g_619

; __device__ __forceinline__ f32x4 mfma16(bf16x8 a, bf16x8 b, f32x4 c) { return __builtin_amdgcn_mfma_f32_16x16x32_bf16(a, b, c, 0, 0, 0); }
; template <class Epi>
; __device__ __forceinline__ void gemm_tile(const bf16_t* __restrict__ A, const bf16_t* __restrict__ Bt, int K, int row0, int col0, const Epi& epi, char* smem,
;                                           bool prefetched, bool nvalid, int nrow0, int ncol0) {
;     ...
;     for (int kt = 0; kt < nk; ++kt) {
;         const int cur = kt & 1;
;         if (kt + 1 < nk) GLDS_STAGE(cur ^ 1, pA, pB, kt + 1);
;         const char* cb = smem + cur * 2 * TILE_B;
; #pragma unroll
;         for (int ks = 0; ks < 2; ++ks) {
;             bf16x8 a[4], b[4];
; #pragma unroll
;             for (int m = 0; m < 4; ++m) a[m] = *(const bf16x8*)(cb + offA[m][ks]);
; #pragma unroll
;             for (int n = 0; n < 4; ++n) b[n] = *(const bf16x8*)(cb + offB[n][ks]);
; #pragma unroll
;             for (int m = 0; m < 4; ++m)
; #pragma unroll
;                 for (int n = 0; n < 4; ++n) acc[m][n] = mfma16(b[n], a[m], acc[m][n]);
;         }
;         asm volatile("s_waitcnt vmcnt(0)" ::: "memory");
;         __syncthreads();
.Lgk_g_619:
.Lgk_loop_619:
	s_and_b32 s3, s1, 0x8000
	s_xor_b32 s10, s3, 0x8000
	v_or_b32_e32 v129, s3, v111
	v_add_u32_e32 v130, s3, v109
	s_add_i32 m0, s11, 0x4000
	s_nop 0
	s_waitcnt lgkmcnt(6)
	v_mfma_f32_16x16x32_bf16 v[0:3], v[92:95], v[174:177], v[0:3]
	global_load_lds_dwordx4 v255, s[100:101]
	ds_read_b128 v[142:145], v129 offset:16384
	s_waitcnt lgkmcnt(6)
	v_mfma_f32_16x16x32_bf16 v[4:7], v[96:99], v[174:177], v[4:7]
	ds_read_b128 v[162:165], v129 offset:16896
	s_add_i32 m0, s11, 0x5000
	s_add_u32 s8, s100, s13
	s_addc_u32 s9, s101, 0
	s_waitcnt lgkmcnt(6)
	v_mfma_f32_16x16x32_bf16 v[8:11], v[100:103], v[174:177], v[8:11]
	global_load_lds_dwordx4 v255, s[8:9]
	ds_read_b128 v[166:169], v129 offset:20480
	s_waitcnt lgkmcnt(6)
	v_mfma_f32_16x16x32_bf16 v[12:15], v[104:107], v[174:177], v[12:15]
	ds_read_b128 v[170:173], v129 offset:20992
	ds_read_b128 v[174:177], v130
	s_add_i32 m0, s11, 0x6000
	s_add_u32 s8, s8, s13
	s_addc_u32 s9, s9, 0
	s_waitcnt lgkmcnt(7)
	v_mfma_f32_16x16x32_bf16 v[16:19], v[92:95], v[178:181], v[16:19]
	global_load_lds_dwordx4 v255, s[8:9]
	v_mfma_f32_16x16x32_bf16 v[20:23], v[96:99], v[178:181], v[20:23]
	s_add_i32 m0, s11, 0x7000
	s_add_u32 s8, s8, s13
	s_addc_u32 s9, s9, 0
	v_mfma_f32_16x16x32_bf16 v[24:27], v[100:103], v[178:181], v[24:27]
	global_load_lds_dwordx4 v255, s[8:9]
	s_add_u32 s100, s100, 0x80
	s_addc_u32 s101, s101, 0
	v_mfma_f32_16x16x32_bf16 v[28:31], v[104:107], v[178:181], v[28:31]
	ds_read_b128 v[178:181], v130 offset:2048
	s_waitcnt lgkmcnt(7)
	v_mfma_f32_16x16x32_bf16 v[32:35], v[92:95], v[246:249], v[32:35]
	v_mfma_f32_16x16x32_bf16 v[36:39], v[96:99], v[246:249], v[36:39]
	v_mfma_f32_16x16x32_bf16 v[40:43], v[100:103], v[246:249], v[40:43]
	v_mfma_f32_16x16x32_bf16 v[44:47], v[104:107], v[246:249], v[44:47]
	ds_read_b128 v[246:249], v130 offset:4096
	s_waitcnt lgkmcnt(7)
	v_mfma_f32_16x16x32_bf16 v[48:51], v[92:95], v[250:253], v[48:51]
	v_mfma_f32_16x16x32_bf16 v[52:55], v[96:99], v[250:253], v[52:55]
	v_mfma_f32_16x16x32_bf16 v[56:59], v[100:103], v[250:253], v[56:59]
	v_mfma_f32_16x16x32_bf16 v[60:63], v[104:107], v[250:253], v[60:63]
	ds_read_b128 v[250:253], v130 offset:6144
	s_waitcnt lgkmcnt(3)
	v_mfma_f32_16x16x32_bf16 v[0:3], v[142:145], v[174:177], v[0:3]
	v_mfma_f32_16x16x32_bf16 v[4:7], v[162:165], v[174:177], v[4:7]
	v_mfma_f32_16x16x32_bf16 v[8:11], v[166:169], v[174:177], v[8:11]
	v_mfma_f32_16x16x32_bf16 v[12:15], v[170:173], v[174:177], v[12:15]
	s_waitcnt lgkmcnt(2)
	v_mfma_f32_16x16x32_bf16 v[16:19], v[142:145], v[178:181], v[16:19]
	v_mfma_f32_16x16x32_bf16 v[20:23], v[162:165], v[178:181], v[20:23]
	v_mfma_f32_16x16x32_bf16 v[24:27], v[166:169], v[178:181], v[24:27]
	v_mfma_f32_16x16x32_bf16 v[28:31], v[170:173], v[178:181], v[28:31]
	s_waitcnt vmcnt(0)
	s_waitcnt lgkmcnt(0)
	s_barrier
	s_add_i32 s1, s1, 0x8000
	s_cmp_eq_u32 s1, 0x1f8000
	s_cbranch_scc1 .Lgk_tail_619
	v_or_b32_e32 v129, s10, v110
	v_add_u32_e32 v130, s10, v108
	s_add_i32 s11, s3, s12
	ds_read_b128 v[174:177], v130
	ds_read_b128 v[92:95], v129 offset:16384
	s_mov_b32 m0, s11
	s_nop 0
	v_mfma_f32_16x16x32_bf16 v[32:35], v[142:145], v[246:249], v[32:35]
	global_load_lds_dwordx4 v254, s[98:99]
	ds_read_b128 v[96:99], v129 offset:16896
	v_mfma_f32_16x16x32_bf16 v[36:39], v[162:165], v[246:249], v[36:39]
	ds_read_b128 v[100:103], v129 offset:20480
	s_add_i32 m0, s11, 0x1000
	s_add_u32 s8, s98, s13
	s_addc_u32 s9, s99, 0
	v_mfma_f32_16x16x32_bf16 v[40:43], v[166:169], v[246:249], v[40:43]
	global_load_lds_dwordx4 v254, s[8:9]
	ds_read_b128 v[104:107], v129 offset:20992
	v_mfma_f32_16x16x32_bf16 v[44:47], v[170:173], v[246:249], v[44:47]
	ds_read_b128 v[178:181], v130 offset:2048
	ds_read_b128 v[246:249], v130 offset:4096
	s_add_i32 m0, s11, 0x2000
	s_add_u32 s8, s8, s13
	s_addc_u32 s9, s9, 0
	v_mfma_f32_16x16x32_bf16 v[48:51], v[142:145], v[250:253], v[48:51]
	global_load_lds_dwordx4 v254, s[8:9]
	v_mfma_f32_16x16x32_bf16 v[52:55], v[162:165], v[250:253], v[52:55]
	s_add_i32 m0, s11, 0x3000
	s_add_u32 s8, s8, s13
	s_addc_u32 s9, s9, 0
	v_mfma_f32_16x16x32_bf16 v[56:59], v[166:169], v[250:253], v[56:59]
	global_load_lds_dwordx4 v254, s[8:9]
	s_add_u32 s98, s98, 0x80
	s_addc_u32 s99, s99, 0
	v_mfma_f32_16x16x32_bf16 v[60:63], v[170:173], v[250:253], v[60:63]
	ds_read_b128 v[250:253], v130 offset:6144
	s_branch .Lgk_loop_619

; template <class Epi>
; __device__ __forceinline__ void gemm_tile(const bf16_t* __restrict__ A, const bf16_t* __restrict__ Bt, int K, int row0, int col0, const Epi& epi, char* smem,
;                                           bool prefetched, bool nvalid, int nrow0, int ncol0) {
;     ...
;     int offA[4][2], offB[4][2];
; #pragma unroll
;     for (int m = 0; m < 4; ++m)
; #pragma unroll
;         for (int ks = 0; ks < 2; ++ks) { const int cx = ((ks * 4 + fq) ^ ((fr >> 1) & 7)) * 16;
;             offA[m][ks] = (wr * 64 + m * 16 + fr) * 128 + cx;
;             offB[m][ks] = TILE_B + (wc * 64 + (m >> 1) * 32 + 8 * (fr >> 2) + 4 * (m & 1) + (fr & 3)) * 128 + cx; }
;     if (prefetched) {
;         if (Epi::STAGED) asm volatile("s_waitcnt vmcnt(8)" ::: "memory");
;         else asm volatile("s_waitcnt vmcnt(0)" ::: "memory");
;     } else {
;         GLDS_STAGE(0, pA, pB, 0);
;         asm volatile("s_waitcnt vmcnt(0)" ::: "memory");
;     }
;     __syncthreads();
;     const int nk = K >> 6;
;     for (int kt = 0; kt < nk; ++kt) {
;         const int cur = kt & 1;
;         if (kt + 1 < nk) GLDS_STAGE(cur ^ 1, pA, pB, kt + 1);
;         const char* cb = smem + cur * 2 * TILE_B;
; #pragma unroll
;         for (int ks = 0; ks < 2; ++ks) {
;             bf16x8 a[4], b[4];
; #pragma unroll
;             for (int m = 0; m < 4; ++m) a[m] = *(const bf16x8*)(cb + offA[m][ks]);
; #pragma unroll
;             for (int n = 0; n < 4; ++n) b[n] = *(const bf16x8*)(cb + offB[n][ks]);
.LBB0_723:
	v_readfirstlane_b32 s98, v64
	v_readfirstlane_b32 s99, v65
	v_readfirstlane_b32 s12, v66
	v_readfirstlane_b32 s100, v72
	v_readfirstlane_b32 s101, v73
	v_readfirstlane_b32 s15, v149
	s_nop 3
	s_sub_u32 s16, s12, s98
	s_and_b32 s98, s98, 0xffffff80
	s_and_b32 s100, s100, 0xffffff80
	s_nop 1
	v_subrev_u32_e32 v254, s98, v64
	v_subrev_u32_e32 v255, s100, v72
	s_add_i32 s14, s15, 0x8000
	s_mov_b32 m0, s14
	s_nop 0
	global_load_lds_dwordx4 v254, s[98:99]
	s_add_i32 m0, s14, 0x1000
	s_add_u32 s12, s98, s16
	s_addc_u32 s13, s99, 0
	global_load_lds_dwordx4 v254, s[12:13]
	s_add_i32 m0, s14, 0x2000
	s_add_u32 s12, s12, s16
	s_addc_u32 s13, s13, 0
	global_load_lds_dwordx4 v254, s[12:13]
	s_add_i32 m0, s14, 0x3000
	s_add_u32 s12, s12, s16
	s_addc_u32 s13, s13, 0
	global_load_lds_dwordx4 v254, s[12:13]
	s_add_u32 s98, s98, 0x80
	s_addc_u32 s99, s99, 0
	ds_read_b128 v[188:191], v137
	ds_read_b128 v[64:67], v143 offset:16384
	ds_read_b128 v[68:71], v143 offset:16896
	ds_read_b128 v[72:75], v143 offset:20480
	ds_read_b128 v[76:79], v143 offset:20992
	ds_read_b128 v[192:195], v137 offset:2048
	ds_read_b128 v[246:249], v137 offset:4096
	ds_read_b128 v[250:253], v137 offset:6144
	v_readlane_b32 s10, v245, 0
	s_nop 3
	s_bitcmp1_b32 s10, 8
	s_cbranch_scc1 .Lgk_y_723
	s_setprio 1
	s_branch .Lgk_g_723

; __device__ __forceinline__ f32x4 mfma16(bf16x8 a, bf16x8 b, f32x4 c) { return __builtin_amdgcn_mfma_f32_16x16x32_bf16(a, b, c, 0, 0, 0); }
; template <class Epi>
; __device__ __forceinline__ void gemm_tile(const bf16_t* __restrict__ A, const bf16_t* __restrict__ Bt, int K, int row0, int col0, const Epi& epi, char* smem,
;                                           bool prefetched, bool nvalid, int nrow0, int ncol0) {
;     ...
;     for (int kt = 0; kt < nk; ++kt) {
;         const int cur = kt & 1;
;         if (kt + 1 < nk) GLDS_STAGE(cur ^ 1, pA, pB, kt + 1);
;         const char* cb = smem + cur * 2 * TILE_B;
; #pragma unroll
;         for (int ks = 0; ks < 2; ++ks) {
;             bf16x8 a[4], b[4];
; #pragma unroll
;             for (int m = 0; m < 4; ++m) a[m] = *(const bf16x8*)(cb + offA[m][ks]);
; #pragma unroll
;             for (int n = 0; n < 4; ++n) b[n] = *(const bf16x8*)(cb + offB[n][ks]);
; #pragma unroll
;             for (int m = 0; m < 4; ++m)
; #pragma unroll
;                 for (int n = 0; n < 4; ++n) acc[m][n] = mfma16(b[n], a[m], acc[m][n]);
;         }
;         asm volatile("s_waitcnt vmcnt(0)" ::: "memory");
;         __syncthreads();
.Lgk_g_723:
.Lgk_loop_723:
	s_and_b32 s10, s7, 0x8000
	s_xor_b32 s11, s10, 0x8000
	v_or_b32_e32 v179, s10, v142
	v_add_u32_e32 v196, s10, v141
	s_add_i32 m0, s14, 0x4000
	s_nop 0
	s_waitcnt lgkmcnt(6)
	v_mfma_f32_16x16x32_bf16 v[0:3], v[64:67], v[188:191], v[0:3]
	global_load_lds_dwordx4 v255, s[100:101]
	ds_read_b128 v[80:83], v179 offset:16384
	s_waitcnt lgkmcnt(6)
	v_mfma_f32_16x16x32_bf16 v[4:7], v[68:71], v[188:191], v[4:7]
	ds_read_b128 v[128:131], v179 offset:16896
	s_add_i32 m0, s14, 0x5000
	s_add_u32 s12, s100, s16
	s_addc_u32 s13, s101, 0
	s_waitcnt lgkmcnt(6)
	v_mfma_f32_16x16x32_bf16 v[8:11], v[72:75], v[188:191], v[8:11]
	global_load_lds_dwordx4 v255, s[12:13]
	ds_read_b128 v[180:183], v179 offset:20480
	s_waitcnt lgkmcnt(6)
	v_mfma_f32_16x16x32_bf16 v[12:15], v[76:79], v[188:191], v[12:15]
	ds_read_b128 v[184:187], v179 offset:20992
	ds_read_b128 v[188:191], v196
	s_add_i32 m0, s14, 0x6000
	s_add_u32 s12, s12, s16
	s_addc_u32 s13, s13, 0
	s_waitcnt lgkmcnt(7)
	v_mfma_f32_16x16x32_bf16 v[16:19], v[64:67], v[192:195], v[16:19]
	global_load_lds_dwordx4 v255, s[12:13]
	v_mfma_f32_16x16x32_bf16 v[20:23], v[68:71], v[192:195], v[20:23]
	s_add_i32 m0, s14, 0x7000
	s_add_u32 s12, s12, s16
	s_addc_u32 s13, s13, 0
	v_mfma_f32_16x16x32_bf16 v[24:27], v[72:75], v[192:195], v[24:27]
	global_load_lds_dwordx4 v255, s[12:13]
	s_add_u32 s100, s100, 0x80
	s_addc_u32 s101, s101, 0
	v_mfma_f32_16x16x32_bf16 v[28:31], v[76:79], v[192:195], v[28:31]
	ds_read_b128 v[192:195], v196 offset:2048
	s_waitcnt lgkmcnt(7)
	v_mfma_f32_16x16x32_bf16 v[32:35], v[64:67], v[246:249], v[32:35]
	v_mfma_f32_16x16x32_bf16 v[36:39], v[68:71], v[246:249], v[36:39]
	v_mfma_f32_16x16x32_bf16 v[40:43], v[72:75], v[246:249], v[40:43]
	v_mfma_f32_16x16x32_bf16 v[44:47], v[76:79], v[246:249], v[44:47]
	ds_read_b128 v[246:249], v196 offset:4096
	s_waitcnt lgkmcnt(7)
	v_mfma_f32_16x16x32_bf16 v[48:51], v[64:67], v[250:253], v[48:51]
	v_mfma_f32_16x16x32_bf16 v[52:55], v[68:71], v[250:253], v[52:55]
	v_mfma_f32_16x16x32_bf16 v[56:59], v[72:75], v[250:253], v[56:59]
	v_mfma_f32_16x16x32_bf16 v[60:63], v[76:79], v[250:253], v[60:63]
	ds_read_b128 v[250:253], v196 offset:6144
	s_waitcnt lgkmcnt(3)
	v_mfma_f32_16x16x32_bf16 v[0:3], v[80:83], v[188:191], v[0:3]
	v_mfma_f32_16x16x32_bf16 v[4:7], v[128:131], v[188:191], v[4:7]
	v_mfma_f32_16x16x32_bf16 v[8:11], v[180:183], v[188:191], v[8:11]
	v_mfma_f32_16x16x32_bf16 v[12:15], v[184:187], v[188:191], v[12:15]
	s_waitcnt lgkmcnt(2)
	v_mfma_f32_16x16x32_bf16 v[16:19], v[80:83], v[192:195], v[16:19]
	v_mfma_f32_16x16x32_bf16 v[20:23], v[128:131], v[192:195], v[20:23]
	v_mfma_f32_16x16x32_bf16 v[24:27], v[180:183], v[192:195], v[24:27]
	v_mfma_f32_16x16x32_bf16 v[28:31], v[184:187], v[192:195], v[28:31]
	s_waitcnt vmcnt(0)
	s_waitcnt lgkmcnt(0)
	s_barrier
	s_add_i32 s7, s7, 0x8000
	s_cmp_eq_u32 s7, 0x78000
	s_cbranch_scc1 .Lgk_tail_723
	v_or_b32_e32 v179, s11, v143
	v_add_u32_e32 v196, s11, v137
	s_add_i32 s14, s10, s15
	ds_read_b128 v[188:191], v196
	ds_read_b128 v[64:67], v179 offset:16384
	s_mov_b32 m0, s14
	s_nop 0
	v_mfma_f32_16x16x32_bf16 v[32:35], v[80:83], v[246:249], v[32:35]
	global_load_lds_dwordx4 v254, s[98:99]
	ds_read_b128 v[68:71], v179 offset:16896
	v_mfma_f32_16x16x32_bf16 v[36:39], v[128:131], v[246:249], v[36:39]
	ds_read_b128 v[72:75], v179 offset:20480
	s_add_i32 m0, s14, 0x1000
	s_add_u32 s12, s98, s16
	s_addc_u32 s13, s99, 0
	v_mfma_f32_16x16x32_bf16 v[40:43], v[180:183], v[246:249], v[40:43]
	global_load_lds_dwordx4 v254, s[12:13]
	ds_read_b128 v[76:79], v179 offset:20992
	v_mfma_f32_16x16x32_bf16 v[44:47], v[184:187], v[246:249], v[44:47]
	ds_read_b128 v[192:195], v196 offset:2048
	ds_read_b128 v[246:249], v196 offset:4096
	s_add_i32 m0, s14, 0x2000
	s_add_u32 s12, s12, s16
	s_addc_u32 s13, s13, 0
	v_mfma_f32_16x16x32_bf16 v[48:51], v[80:83], v[250:253], v[48:51]
	global_load_lds_dwordx4 v254, s[12:13]
	v_mfma_f32_16x16x32_bf16 v[52:55], v[128:131], v[250:253], v[52:55]
	s_add_i32 m0, s14, 0x3000
	s_add_u32 s12, s12, s16
	s_addc_u32 s13, s13, 0
	v_mfma_f32_16x16x32_bf16 v[56:59], v[180:183], v[250:253], v[56:59]
	global_load_lds_dwordx4 v254, s[12:13]
	s_add_u32 s98, s98, 0x80
	s_addc_u32 s99, s99, 0
	v_mfma_f32_16x16x32_bf16 v[60:63], v[184:187], v[250:253], v[60:63]
	ds_read_b128 v[250:253], v196 offset:6144
	s_branch .Lgk_loop_723

; template <class Epi>
; __device__ __forceinline__ void gemm_tile(const bf16_t* __restrict__ A, const bf16_t* __restrict__ Bt, int K, int row0, int col0, const Epi& epi, char* smem,
;                                           bool prefetched, bool nvalid, int nrow0, int ncol0) {
;     ...
;     int offA[4][2], offB[4][2];
; #pragma unroll
;     for (int m = 0; m < 4; ++m)
; #pragma unroll
;         for (int ks = 0; ks < 2; ++ks) { const int cx = ((ks * 4 + fq) ^ ((fr >> 1) & 7)) * 16;
;             offA[m][ks] = (wr * 64 + m * 16 + fr) * 128 + cx;
;             offB[m][ks] = TILE_B + (wc * 64 + (m >> 1) * 32 + 8 * (fr >> 2) + 4 * (m & 1) + (fr & 3)) * 128 + cx; }
;     if (prefetched) {
;         if (Epi::STAGED) asm volatile("s_waitcnt vmcnt(8)" ::: "memory");
;         else asm volatile("s_waitcnt vmcnt(0)" ::: "memory");
;     } else {
;         GLDS_STAGE(0, pA, pB, 0);
;         asm volatile("s_waitcnt vmcnt(0)" ::: "memory");
;     }
;     __syncthreads();
;     const int nk = K >> 6;
;     for (int kt = 0; kt < nk; ++kt) {
;         const int cur = kt & 1;
;         if (kt + 1 < nk) GLDS_STAGE(cur ^ 1, pA, pB, kt + 1);
;         const char* cb = smem + cur * 2 * TILE_B;
; #pragma unroll
;         for (int ks = 0; ks < 2; ++ks) {
;             bf16x8 a[4], b[4];
; #pragma unroll
;             for (int m = 0; m < 4; ++m) a[m] = *(const bf16x8*)(cb + offA[m][ks]);
; #pragma unroll
;             for (int n = 0; n < 4; ++n) b[n] = *(const bf16x8*)(cb + offB[n][ks]);
.LBB0_766:
	v_readfirstlane_b32 s98, v106
	v_readfirstlane_b32 s99, v107
	v_readfirstlane_b32 s10, v108
	v_readfirstlane_b32 s100, v120
	v_readfirstlane_b32 s101, v121
	v_readfirstlane_b32 s13, v149
	s_nop 3
	s_sub_u32 s16, s10, s98
	s_and_b32 s98, s98, 0xffffff80
	s_and_b32 s100, s100, 0xffffff80
	s_nop 1
	v_subrev_u32_e32 v254, s98, v106
	v_subrev_u32_e32 v255, s100, v120
	s_add_i32 s12, s13, 0x8000
	s_mov_b32 m0, s12
	s_nop 0
	global_load_lds_dwordx4 v254, s[98:99]
	s_add_i32 m0, s12, 0x1000
	s_add_u32 s10, s98, s16
	s_addc_u32 s11, s99, 0
	global_load_lds_dwordx4 v254, s[10:11]
	s_add_i32 m0, s12, 0x2000
	s_add_u32 s10, s10, s16
	s_addc_u32 s11, s11, 0
	global_load_lds_dwordx4 v254, s[10:11]
	s_add_i32 m0, s12, 0x3000
	s_add_u32 s10, s10, s16
	s_addc_u32 s11, s11, 0
	global_load_lds_dwordx4 v254, s[10:11]
	s_add_u32 s98, s98, 0x80
	s_addc_u32 s99, s99, 0
	ds_read_b128 v[190:193], v128
	ds_read_b128 v[106:109], v131 offset:16384
	ds_read_b128 v[118:121], v131 offset:16896
	ds_read_b128 v[122:125], v131 offset:20480
	ds_read_b128 v[170:173], v131 offset:20992
	ds_read_b128 v[194:197], v128 offset:2048
	ds_read_b128 v[198:201], v128 offset:4096
	ds_read_b128 v[246:249], v128 offset:6144
	v_readlane_b32 s8, v245, 0
	s_nop 3
	s_bitcmp1_b32 s8, 8
	s_cbranch_scc1 .Lgk_y_766
	s_setprio 1
	s_branch .Lgk_g_766

; __device__ __forceinline__ f32x4 mfma16(bf16x8 a, bf16x8 b, f32x4 c) { return __builtin_amdgcn_mfma_f32_16x16x32_bf16(a, b, c, 0, 0, 0); }
; template <class Epi>
; __device__ __forceinline__ void gemm_tile(const bf16_t* __restrict__ A, const bf16_t* __restrict__ Bt, int K, int row0, int col0, const Epi& epi, char* smem,
;                                           bool prefetched, bool nvalid, int nrow0, int ncol0) {
;     ...
;     for (int kt = 0; kt < nk; ++kt) {
;         const int cur = kt & 1;
;         if (kt + 1 < nk) GLDS_STAGE(cur ^ 1, pA, pB, kt + 1);
;         const char* cb = smem + cur * 2 * TILE_B;
; #pragma unroll
;         for (int ks = 0; ks < 2; ++ks) {
;             bf16x8 a[4], b[4];
; #pragma unroll
;             for (int m = 0; m < 4; ++m) a[m] = *(const bf16x8*)(cb + offA[m][ks]);
; #pragma unroll
;             for (int n = 0; n < 4; ++n) b[n] = *(const bf16x8*)(cb + offB[n][ks]);
; #pragma unroll
;             for (int m = 0; m < 4; ++m)
; #pragma unroll
;                 for (int n = 0; n < 4; ++n) acc[m][n] = mfma16(b[n], a[m], acc[m][n]);
;         }
;         asm volatile("s_waitcnt vmcnt(0)" ::: "memory");
;         __syncthreads();
.Lgk_g_766:
.Lgk_loop_766:
	s_and_b32 s8, s1, 0x8000
	s_xor_b32 s9, s8, 0x8000
	v_or_b32_e32 v164, s8, v130
	v_add_u32_e32 v165, s8, v129
	s_add_i32 m0, s12, 0x4000
	s_nop 0
	s_waitcnt lgkmcnt(6)
	v_mfma_f32_16x16x32_bf16 v[0:3], v[106:109], v[190:193], v[0:3]
	global_load_lds_dwordx4 v255, s[100:101]
	ds_read_b128 v[174:177], v164 offset:16384
	s_waitcnt lgkmcnt(6)
	v_mfma_f32_16x16x32_bf16 v[4:7], v[118:121], v[190:193], v[4:7]
	ds_read_b128 v[178:181], v164 offset:16896
	s_add_i32 m0, s12, 0x5000
	s_add_u32 s10, s100, s16
	s_addc_u32 s11, s101, 0
	s_waitcnt lgkmcnt(6)
	v_mfma_f32_16x16x32_bf16 v[8:11], v[122:125], v[190:193], v[8:11]
	global_load_lds_dwordx4 v255, s[10:11]
	ds_read_b128 v[182:185], v164 offset:20480
	s_waitcnt lgkmcnt(6)
	v_mfma_f32_16x16x32_bf16 v[12:15], v[170:173], v[190:193], v[12:15]
	ds_read_b128 v[186:189], v164 offset:20992
	ds_read_b128 v[190:193], v165
	s_add_i32 m0, s12, 0x6000
	s_add_u32 s10, s10, s16
	s_addc_u32 s11, s11, 0
	s_waitcnt lgkmcnt(7)
	v_mfma_f32_16x16x32_bf16 v[16:19], v[106:109], v[194:197], v[16:19]
	global_load_lds_dwordx4 v255, s[10:11]
	v_mfma_f32_16x16x32_bf16 v[20:23], v[118:121], v[194:197], v[20:23]
	s_add_i32 m0, s12, 0x7000
	s_add_u32 s10, s10, s16
	s_addc_u32 s11, s11, 0
	v_mfma_f32_16x16x32_bf16 v[24:27], v[122:125], v[194:197], v[24:27]
	global_load_lds_dwordx4 v255, s[10:11]
	s_add_u32 s100, s100, 0x80
	s_addc_u32 s101, s101, 0
	v_mfma_f32_16x16x32_bf16 v[28:31], v[170:173], v[194:197], v[28:31]
	ds_read_b128 v[194:197], v165 offset:2048
	s_waitcnt lgkmcnt(7)
	v_mfma_f32_16x16x32_bf16 v[32:35], v[106:109], v[198:201], v[32:35]
	v_mfma_f32_16x16x32_bf16 v[36:39], v[118:121], v[198:201], v[36:39]
	v_mfma_f32_16x16x32_bf16 v[40:43], v[122:125], v[198:201], v[40:43]
	v_mfma_f32_16x16x32_bf16 v[44:47], v[170:173], v[198:201], v[44:47]
	ds_read_b128 v[198:201], v165 offset:4096
	s_waitcnt lgkmcnt(7)
	v_mfma_f32_16x16x32_bf16 v[48:51], v[106:109], v[246:249], v[48:51]
	v_mfma_f32_16x16x32_bf16 v[52:55], v[118:121], v[246:249], v[52:55]
	v_mfma_f32_16x16x32_bf16 v[56:59], v[122:125], v[246:249], v[56:59]
	v_mfma_f32_16x16x32_bf16 v[60:63], v[170:173], v[246:249], v[60:63]
	ds_read_b128 v[246:249], v165 offset:6144
	s_waitcnt lgkmcnt(3)
	v_mfma_f32_16x16x32_bf16 v[0:3], v[174:177], v[190:193], v[0:3]
	v_mfma_f32_16x16x32_bf16 v[4:7], v[178:181], v[190:193], v[4:7]
	v_mfma_f32_16x16x32_bf16 v[8:11], v[182:185], v[190:193], v[8:11]
	v_mfma_f32_16x16x32_bf16 v[12:15], v[186:189], v[190:193], v[12:15]
	s_waitcnt lgkmcnt(2)
	v_mfma_f32_16x16x32_bf16 v[16:19], v[174:177], v[194:197], v[16:19]
	v_mfma_f32_16x16x32_bf16 v[20:23], v[178:181], v[194:197], v[20:23]
	v_mfma_f32_16x16x32_bf16 v[24:27], v[182:185], v[194:197], v[24:27]
	v_mfma_f32_16x16x32_bf16 v[28:31], v[186:189], v[194:197], v[28:31]
	s_waitcnt vmcnt(0)
	s_waitcnt lgkmcnt(0)
	s_barrier
	s_add_i32 s1, s1, 0x8000
	s_cmp_eq_u32 s1, 0x78000
	s_cbranch_scc1 .Lgk_tail_766
	v_or_b32_e32 v164, s9, v131
	v_add_u32_e32 v165, s9, v128
	s_add_i32 s12, s8, s13
	ds_read_b128 v[190:193], v165
	ds_read_b128 v[106:109], v164 offset:16384
	s_mov_b32 m0, s12
	s_nop 0
	v_mfma_f32_16x16x32_bf16 v[32:35], v[174:177], v[198:201], v[32:35]
	global_load_lds_dwordx4 v254, s[98:99]
	ds_read_b128 v[118:121], v164 offset:16896
	v_mfma_f32_16x16x32_bf16 v[36:39], v[178:181], v[198:201], v[36:39]
	ds_read_b128 v[122:125], v164 offset:20480
	s_add_i32 m0, s12, 0x1000
	s_add_u32 s10, s98, s16
	s_addc_u32 s11, s99, 0
	v_mfma_f32_16x16x32_bf16 v[40:43], v[182:185], v[198:201], v[40:43]
	global_load_lds_dwordx4 v254, s[10:11]
	ds_read_b128 v[170:173], v164 offset:20992
	v_mfma_f32_16x16x32_bf16 v[44:47], v[186:189], v[198:201], v[44:47]
	ds_read_b128 v[194:197], v165 offset:2048
	ds_read_b128 v[198:201], v165 offset:4096
	s_add_i32 m0, s12, 0x2000
	s_add_u32 s10, s10, s16
	s_addc_u32 s11, s11, 0
	v_mfma_f32_16x16x32_bf16 v[48:51], v[174:177], v[246:249], v[48:51]
	global_load_lds_dwordx4 v254, s[10:11]
	v_mfma_f32_16x16x32_bf16 v[52:55], v[178:181], v[246:249], v[52:55]
	s_add_i32 m0, s12, 0x3000
	s_add_u32 s10, s10, s16
	s_addc_u32 s11, s11, 0
	v_mfma_f32_16x16x32_bf16 v[56:59], v[182:185], v[246:249], v[56:59]
	global_load_lds_dwordx4 v254, s[10:11]
	s_add_u32 s98, s98, 0x80
	s_addc_u32 s99, s99, 0
	v_mfma_f32_16x16x32_bf16 v[60:63], v[186:189], v[246:249], v[60:63]
	ds_read_b128 v[246:249], v165 offset:6144
	s_branch .Lgk_loop_766

; __device__ __forceinline__ f32x4 mfma16(bf16x8 a, bf16x8 b, f32x4 c) { return __builtin_amdgcn_mfma_f32_16x16x32_bf16(a, b, c, 0, 0, 0); }
; template <class Epi>
; __device__ __forceinline__ void gemm_tile(const bf16_t* __restrict__ A, const bf16_t* __restrict__ Bt, int K, int row0, int col0, const Epi& epi, char* smem,
;                                           bool prefetched, bool nvalid, int nrow0, int ncol0) {
;     ...
;     for (int kt = 0; kt < nk; ++kt) {
;         const int cur = kt & 1;
;         if (kt + 1 < nk) GLDS_STAGE(cur ^ 1, pA, pB, kt + 1);
;         const char* cb = smem + cur * 2 * TILE_B;
; #pragma unroll
;         for (int ks = 0; ks < 2; ++ks) {
;             bf16x8 a[4], b[4];
; #pragma unroll
;             for (int m = 0; m < 4; ++m) a[m] = *(const bf16x8*)(cb + offA[m][ks]);
; #pragma unroll
;             for (int n = 0; n < 4; ++n) b[n] = *(const bf16x8*)(cb + offB[n][ks]);
; #pragma unroll
;             for (int m = 0; m < 4; ++m)
; #pragma unroll
;                 for (int n = 0; n < 4; ++n) acc[m][n] = mfma16(b[n], a[m], acc[m][n]);
;         }
;         asm volatile("s_waitcnt vmcnt(0)" ::: "memory");
;         __syncthreads();
.Lgk_g_895:
.Lgk_loop_895:
	s_and_b32 s3, s1, 0x8000
	s_xor_b32 s10, s3, 0x8000
	v_or_b32_e32 v131, s3, v111
	v_add_u32_e32 v144, s3, v109
	s_add_i32 m0, s11, 0x4000
	s_nop 0
	s_waitcnt lgkmcnt(6)
	v_mfma_f32_16x16x32_bf16 v[0:3], v[92:95], v[174:177], v[0:3]
	global_load_lds_dwordx4 v255, s[100:101]
	ds_read_b128 v[132:135], v131 offset:16384
	s_waitcnt lgkmcnt(6)
	v_mfma_f32_16x16x32_bf16 v[4:7], v[96:99], v[174:177], v[4:7]
	ds_read_b128 v[136:139], v131 offset:16896
	s_add_i32 m0, s11, 0x5000
	s_add_u32 s8, s100, s13
	s_addc_u32 s9, s101, 0
	s_waitcnt lgkmcnt(6)
	v_mfma_f32_16x16x32_bf16 v[8:11], v[100:103], v[174:177], v[8:11]
	global_load_lds_dwordx4 v255, s[8:9]
	ds_read_b128 v[140:143], v131 offset:20480
	s_waitcnt lgkmcnt(6)
	v_mfma_f32_16x16x32_bf16 v[12:15], v[104:107], v[174:177], v[12:15]
	ds_read_b128 v[170:173], v131 offset:20992
	ds_read_b128 v[174:177], v144
	s_add_i32 m0, s11, 0x6000
	s_add_u32 s8, s8, s13
	s_addc_u32 s9, s9, 0
	s_waitcnt lgkmcnt(7)
	v_mfma_f32_16x16x32_bf16 v[16:19], v[92:95], v[178:181], v[16:19]
	global_load_lds_dwordx4 v255, s[8:9]
	v_mfma_f32_16x16x32_bf16 v[20:23], v[96:99], v[178:181], v[20:23]
	s_add_i32 m0, s11, 0x7000
	s_add_u32 s8, s8, s13
	s_addc_u32 s9, s9, 0
	v_mfma_f32_16x16x32_bf16 v[24:27], v[100:103], v[178:181], v[24:27]
	global_load_lds_dwordx4 v255, s[8:9]
	s_add_u32 s100, s100, 0x80
	s_addc_u32 s101, s101, 0
	v_mfma_f32_16x16x32_bf16 v[28:31], v[104:107], v[178:181], v[28:31]
	ds_read_b128 v[178:181], v144 offset:2048
	s_waitcnt lgkmcnt(7)
	v_mfma_f32_16x16x32_bf16 v[32:35], v[92:95], v[246:249], v[32:35]
	v_mfma_f32_16x16x32_bf16 v[36:39], v[96:99], v[246:249], v[36:39]
	v_mfma_f32_16x16x32_bf16 v[40:43], v[100:103], v[246:249], v[40:43]
	v_mfma_f32_16x16x32_bf16 v[44:47], v[104:107], v[246:249], v[44:47]
	ds_read_b128 v[246:249], v144 offset:4096
	s_waitcnt lgkmcnt(7)
	v_mfma_f32_16x16x32_bf16 v[48:51], v[92:95], v[250:253], v[48:51]
	v_mfma_f32_16x16x32_bf16 v[52:55], v[96:99], v[250:253], v[52:55]
	v_mfma_f32_16x16x32_bf16 v[56:59], v[100:103], v[250:253], v[56:59]
	v_mfma_f32_16x16x32_bf16 v[60:63], v[104:107], v[250:253], v[60:63]
	ds_read_b128 v[250:253], v144 offset:6144
	s_waitcnt lgkmcnt(3)
	v_mfma_f32_16x16x32_bf16 v[0:3], v[132:135], v[174:177], v[0:3]
	v_mfma_f32_16x16x32_bf16 v[4:7], v[136:139], v[174:177], v[4:7]
	v_mfma_f32_16x16x32_bf16 v[8:11], v[140:143], v[174:177], v[8:11]
	v_mfma_f32_16x16x32_bf16 v[12:15], v[170:173], v[174:177], v[12:15]
	s_waitcnt lgkmcnt(2)
	v_mfma_f32_16x16x32_bf16 v[16:19], v[132:135], v[178:181], v[16:19]
	v_mfma_f32_16x16x32_bf16 v[20:23], v[136:139], v[178:181], v[20:23]
	v_mfma_f32_16x16x32_bf16 v[24:27], v[140:143], v[178:181], v[24:27]
	v_mfma_f32_16x16x32_bf16 v[28:31], v[170:173], v[178:181], v[28:31]
	s_waitcnt vmcnt(0)
	s_waitcnt lgkmcnt(0)
	s_barrier
	s_add_i32 s1, s1, 0x8000
	s_cmp_eq_u32 s1, 0x78000
	s_cbranch_scc1 .Lgk_tail_895
	v_or_b32_e32 v131, s10, v110
	v_add_u32_e32 v144, s10, v108
	s_add_i32 s11, s3, s12
	ds_read_b128 v[174:177], v144
	ds_read_b128 v[92:95], v131 offset:16384
	s_mov_b32 m0, s11
	s_nop 0
	v_mfma_f32_16x16x32_bf16 v[32:35], v[132:135], v[246:249], v[32:35]
	global_load_lds_dwordx4 v254, s[98:99]
	ds_read_b128 v[96:99], v131 offset:16896
	v_mfma_f32_16x16x32_bf16 v[36:39], v[136:139], v[246:249], v[36:39]
	ds_read_b128 v[100:103], v131 offset:20480
	s_add_i32 m0, s11, 0x1000
	s_add_u32 s8, s98, s13
	s_addc_u32 s9, s99, 0
	v_mfma_f32_16x16x32_bf16 v[40:43], v[140:143], v[246:249], v[40:43]
	global_load_lds_dwordx4 v254, s[8:9]
	ds_read_b128 v[104:107], v131 offset:20992
	v_mfma_f32_16x16x32_bf16 v[44:47], v[170:173], v[246:249], v[44:47]
	ds_read_b128 v[178:181], v144 offset:2048
	ds_read_b128 v[246:249], v144 offset:4096
	s_add_i32 m0, s11, 0x2000
	s_add_u32 s8, s8, s13
	s_addc_u32 s9, s9, 0
	v_mfma_f32_16x16x32_bf16 v[48:51], v[132:135], v[250:253], v[48:51]
	global_load_lds_dwordx4 v254, s[8:9]
	v_mfma_f32_16x16x32_bf16 v[52:55], v[136:139], v[250:253], v[52:55]
	s_add_i32 m0, s11, 0x3000
	s_add_u32 s8, s8, s13
	s_addc_u32 s9, s9, 0
	v_mfma_f32_16x16x32_bf16 v[56:59], v[140:143], v[250:253], v[56:59]
	global_load_lds_dwordx4 v254, s[8:9]
	s_add_u32 s98, s98, 0x80
	s_addc_u32 s99, s99, 0
	v_mfma_f32_16x16x32_bf16 v[60:63], v[170:173], v[250:253], v[60:63]
	ds_read_b128 v[250:253], v144 offset:6144
	s_branch .Lgk_loop_895

; template <class Epi>
; __device__ __forceinline__ void gemm_tile(const bf16_t* __restrict__ A, const bf16_t* __restrict__ Bt, int K, int row0, int col0, const Epi& epi, char* smem,
;                                           bool prefetched, bool nvalid, int nrow0, int ncol0) {
;     ...
;     int offA[4][2], offB[4][2];
; #pragma unroll
;     for (int m = 0; m < 4; ++m)
; #pragma unroll
;         for (int ks = 0; ks < 2; ++ks) { const int cx = ((ks * 4 + fq) ^ ((fr >> 1) & 7)) * 16;
;             offA[m][ks] = (wr * 64 + m * 16 + fr) * 128 + cx;
;             offB[m][ks] = TILE_B + (wc * 64 + (m >> 1) * 32 + 8 * (fr >> 2) + 4 * (m & 1) + (fr & 3)) * 128 + cx; }
;     if (prefetched) {
;         if (Epi::STAGED) asm volatile("s_waitcnt vmcnt(8)" ::: "memory");
;         else asm volatile("s_waitcnt vmcnt(0)" ::: "memory");
;     } else {
;         GLDS_STAGE(0, pA, pB, 0);
;         asm volatile("s_waitcnt vmcnt(0)" ::: "memory");
;     }
;     __syncthreads();
;     const int nk = K >> 6;
;     for (int kt = 0; kt < nk; ++kt) {
;         const int cur = kt & 1;
;         if (kt + 1 < nk) GLDS_STAGE(cur ^ 1, pA, pB, kt + 1);
;         const char* cb = smem + cur * 2 * TILE_B;
; #pragma unroll
;         for (int ks = 0; ks < 2; ++ks) {
;             bf16x8 a[4], b[4];
; #pragma unroll
;             for (int m = 0; m < 4; ++m) a[m] = *(const bf16x8*)(cb + offA[m][ks]);
; #pragma unroll
;             for (int n = 0; n < 4; ++n) b[n] = *(const bf16x8*)(cb + offB[n][ks]);
.LBB0_998:
	v_readfirstlane_b32 s98, v106
	v_readfirstlane_b32 s99, v107
	v_readfirstlane_b32 s10, v108
	v_readfirstlane_b32 s100, v120
	v_readfirstlane_b32 s101, v121
	v_readfirstlane_b32 s17, v149
	s_nop 3
	s_sub_u32 s18, s10, s98
	s_and_b32 s98, s98, 0xffffff80
	s_and_b32 s100, s100, 0xffffff80
	s_nop 1
	v_subrev_u32_e32 v254, s98, v106
	v_subrev_u32_e32 v255, s100, v120
	s_add_i32 s13, s17, 0x8000
	s_mov_b32 m0, s13
	s_nop 0
	global_load_lds_dwordx4 v254, s[98:99]
	s_add_i32 m0, s13, 0x1000
	s_add_u32 s10, s98, s18
	s_addc_u32 s11, s99, 0
	global_load_lds_dwordx4 v254, s[10:11]
	s_add_i32 m0, s13, 0x2000
	s_add_u32 s10, s10, s18
	s_addc_u32 s11, s11, 0
	global_load_lds_dwordx4 v254, s[10:11]
	s_add_i32 m0, s13, 0x3000
	s_add_u32 s10, s10, s18
	s_addc_u32 s11, s11, 0
	global_load_lds_dwordx4 v254, s[10:11]
	s_add_u32 s98, s98, 0x80
	s_addc_u32 s99, s99, 0
	ds_read_b128 v[184:187], v130
	ds_read_b128 v[106:109], v133 offset:16384
	ds_read_b128 v[118:121], v133 offset:16896
	ds_read_b128 v[122:125], v133 offset:20480
	ds_read_b128 v[158:161], v133 offset:20992
	ds_read_b128 v[188:191], v130 offset:2048
	ds_read_b128 v[246:249], v130 offset:4096
	ds_read_b128 v[250:253], v130 offset:6144
	v_readlane_b32 s9, v245, 0
	s_nop 3
	s_bitcmp1_b32 s9, 8
	s_cbranch_scc1 .Lgk_y_998
	s_setprio 1
	s_branch .Lgk_g_998

; __device__ __forceinline__ f32x4 mfma16(bf16x8 a, bf16x8 b, f32x4 c) { return __builtin_amdgcn_mfma_f32_16x16x32_bf16(a, b, c, 0, 0, 0); }
; template <class Epi>
; __device__ __forceinline__ void gemm_tile(const bf16_t* __restrict__ A, const bf16_t* __restrict__ Bt, int K, int row0, int col0, const Epi& epi, char* smem,
;                                           bool prefetched, bool nvalid, int nrow0, int ncol0) {
;     ...
;     for (int kt = 0; kt < nk; ++kt) {
;         const int cur = kt & 1;
;         if (kt + 1 < nk) GLDS_STAGE(cur ^ 1, pA, pB, kt + 1);
;         const char* cb = smem + cur * 2 * TILE_B;
; #pragma unroll
;         for (int ks = 0; ks < 2; ++ks) {
;             bf16x8 a[4], b[4];
; #pragma unroll
;             for (int m = 0; m < 4; ++m) a[m] = *(const bf16x8*)(cb + offA[m][ks]);
; #pragma unroll
;             for (int n = 0; n < 4; ++n) b[n] = *(const bf16x8*)(cb + offB[n][ks]);
; #pragma unroll
;             for (int m = 0; m < 4; ++m)
; #pragma unroll
;                 for (int n = 0; n < 4; ++n) acc[m][n] = mfma16(b[n], a[m], acc[m][n]);
;         }
;         asm volatile("s_waitcnt vmcnt(0)" ::: "memory");
;         __syncthreads();
.Lgk_g_998:
.Lgk_loop_998:
	s_and_b32 s9, s8, 0x8000
	s_xor_b32 s12, s9, 0x8000
	v_or_b32_e32 v167, s9, v132
	v_add_u32_e32 v110, s9, v131
	s_add_i32 m0, s13, 0x4000
	s_nop 0
	s_waitcnt lgkmcnt(6)
	v_mfma_f32_16x16x32_bf16 v[0:3], v[106:109], v[184:187], v[0:3]
	global_load_lds_dwordx4 v255, s[100:101]
	ds_read_b128 v[168:171], v167 offset:16384
	s_waitcnt lgkmcnt(6)
	v_mfma_f32_16x16x32_bf16 v[4:7], v[118:121], v[184:187], v[4:7]
	ds_read_b128 v[172:175], v167 offset:16896
	s_add_i32 m0, s13, 0x5000
	s_add_u32 s10, s100, s18
	s_addc_u32 s11, s101, 0
	s_waitcnt lgkmcnt(6)
	v_mfma_f32_16x16x32_bf16 v[8:11], v[122:125], v[184:187], v[8:11]
	global_load_lds_dwordx4 v255, s[10:11]
	ds_read_b128 v[176:179], v167 offset:20480
	s_waitcnt lgkmcnt(6)
	v_mfma_f32_16x16x32_bf16 v[12:15], v[158:161], v[184:187], v[12:15]
	ds_read_b128 v[180:183], v167 offset:20992
	ds_read_b128 v[184:187], v110
	s_add_i32 m0, s13, 0x6000
	s_add_u32 s10, s10, s18
	s_addc_u32 s11, s11, 0
	s_waitcnt lgkmcnt(7)
	v_mfma_f32_16x16x32_bf16 v[16:19], v[106:109], v[188:191], v[16:19]
	global_load_lds_dwordx4 v255, s[10:11]
	v_mfma_f32_16x16x32_bf16 v[20:23], v[118:121], v[188:191], v[20:23]
	s_add_i32 m0, s13, 0x7000
	s_add_u32 s10, s10, s18
	s_addc_u32 s11, s11, 0
	v_mfma_f32_16x16x32_bf16 v[24:27], v[122:125], v[188:191], v[24:27]
	global_load_lds_dwordx4 v255, s[10:11]
	s_add_u32 s100, s100, 0x80
	s_addc_u32 s101, s101, 0
	v_mfma_f32_16x16x32_bf16 v[28:31], v[158:161], v[188:191], v[28:31]
	ds_read_b128 v[188:191], v110 offset:2048
	s_waitcnt lgkmcnt(7)
	v_mfma_f32_16x16x32_bf16 v[32:35], v[106:109], v[246:249], v[32:35]
	v_mfma_f32_16x16x32_bf16 v[36:39], v[118:121], v[246:249], v[36:39]
	v_mfma_f32_16x16x32_bf16 v[40:43], v[122:125], v[246:249], v[40:43]
	v_mfma_f32_16x16x32_bf16 v[44:47], v[158:161], v[246:249], v[44:47]
	ds_read_b128 v[246:249], v110 offset:4096
	s_waitcnt lgkmcnt(7)
	v_mfma_f32_16x16x32_bf16 v[48:51], v[106:109], v[250:253], v[48:51]
	v_mfma_f32_16x16x32_bf16 v[52:55], v[118:121], v[250:253], v[52:55]
	v_mfma_f32_16x16x32_bf16 v[56:59], v[122:125], v[250:253], v[56:59]
	v_mfma_f32_16x16x32_bf16 v[60:63], v[158:161], v[250:253], v[60:63]
	ds_read_b128 v[250:253], v110 offset:6144
	s_waitcnt lgkmcnt(3)
	v_mfma_f32_16x16x32_bf16 v[0:3], v[168:171], v[184:187], v[0:3]
	v_mfma_f32_16x16x32_bf16 v[4:7], v[172:175], v[184:187], v[4:7]
	v_mfma_f32_16x16x32_bf16 v[8:11], v[176:179], v[184:187], v[8:11]
	v_mfma_f32_16x16x32_bf16 v[12:15], v[180:183], v[184:187], v[12:15]
	s_waitcnt lgkmcnt(2)
	v_mfma_f32_16x16x32_bf16 v[16:19], v[168:171], v[188:191], v[16:19]
	v_mfma_f32_16x16x32_bf16 v[20:23], v[172:175], v[188:191], v[20:23]
	v_mfma_f32_16x16x32_bf16 v[24:27], v[176:179], v[188:191], v[24:27]
	v_mfma_f32_16x16x32_bf16 v[28:31], v[180:183], v[188:191], v[28:31]
	s_waitcnt vmcnt(0)
	s_waitcnt lgkmcnt(0)
	s_barrier
	s_add_i32 s8, s8, 0x8000
	s_cmp_eq_u32 s8, 0x78000
	s_cbranch_scc1 .Lgk_tail_998
	v_or_b32_e32 v167, s12, v133
	v_add_u32_e32 v110, s12, v130
	s_add_i32 s13, s9, s17
	ds_read_b128 v[184:187], v110
	ds_read_b128 v[106:109], v167 offset:16384
	s_mov_b32 m0, s13
	s_nop 0
	v_mfma_f32_16x16x32_bf16 v[32:35], v[168:171], v[246:249], v[32:35]
	global_load_lds_dwordx4 v254, s[98:99]
	ds_read_b128 v[118:121], v167 offset:16896
	v_mfma_f32_16x16x32_bf16 v[36:39], v[172:175], v[246:249], v[36:39]
	ds_read_b128 v[122:125], v167 offset:20480
	s_add_i32 m0, s13, 0x1000
	s_add_u32 s10, s98, s18
	s_addc_u32 s11, s99, 0
	v_mfma_f32_16x16x32_bf16 v[40:43], v[176:179], v[246:249], v[40:43]
	global_load_lds_dwordx4 v254, s[10:11]
	ds_read_b128 v[158:161], v167 offset:20992
	v_mfma_f32_16x16x32_bf16 v[44:47], v[180:183], v[246:249], v[44:47]
	ds_read_b128 v[188:191], v110 offset:2048
	ds_read_b128 v[246:249], v110 offset:4096
	s_add_i32 m0, s13, 0x2000
	s_add_u32 s10, s10, s18
	s_addc_u32 s11, s11, 0
	v_mfma_f32_16x16x32_bf16 v[48:51], v[168:171], v[250:253], v[48:51]
	global_load_lds_dwordx4 v254, s[10:11]
	v_mfma_f32_16x16x32_bf16 v[52:55], v[172:175], v[250:253], v[52:55]
	s_add_i32 m0, s13, 0x3000
	s_add_u32 s10, s10, s18
	s_addc_u32 s11, s11, 0
	v_mfma_f32_16x16x32_bf16 v[56:59], v[176:179], v[250:253], v[56:59]
	global_load_lds_dwordx4 v254, s[10:11]
	s_add_u32 s98, s98, 0x80
	s_addc_u32 s99, s99, 0
	v_mfma_f32_16x16x32_bf16 v[60:63], v[180:183], v[250:253], v[60:63]
	ds_read_b128 v[250:253], v110 offset:6144
	s_branch .Lgk_loop_998

; template <class Epi>
; __device__ __forceinline__ void gemm_tile(const bf16_t* __restrict__ A, const bf16_t* __restrict__ Bt, int K, int row0, int col0, const Epi& epi, char* smem,
;                                           bool prefetched, bool nvalid, int nrow0, int ncol0) {
;     ...
;     int offA[4][2], offB[4][2];
; #pragma unroll
;     for (int m = 0; m < 4; ++m)
; #pragma unroll
;         for (int ks = 0; ks < 2; ++ks) { const int cx = ((ks * 4 + fq) ^ ((fr >> 1) & 7)) * 16;
;             offA[m][ks] = (wr * 64 + m * 16 + fr) * 128 + cx;
;             offB[m][ks] = TILE_B + (wc * 64 + (m >> 1) * 32 + 8 * (fr >> 2) + 4 * (m & 1) + (fr & 3)) * 128 + cx; }
;     if (prefetched) {
;         if (Epi::STAGED) asm volatile("s_waitcnt vmcnt(8)" ::: "memory");
;         else asm volatile("s_waitcnt vmcnt(0)" ::: "memory");
;     } else {
;         GLDS_STAGE(0, pA, pB, 0);
;         asm volatile("s_waitcnt vmcnt(0)" ::: "memory");
;     }
;     __syncthreads();
;     const int nk = K >> 6;
;     for (int kt = 0; kt < nk; ++kt) {
;         const int cur = kt & 1;
;         if (kt + 1 < nk) GLDS_STAGE(cur ^ 1, pA, pB, kt + 1);
;         const char* cb = smem + cur * 2 * TILE_B;
; #pragma unroll
;         for (int ks = 0; ks < 2; ++ks) {
;             bf16x8 a[4], b[4];
; #pragma unroll
;             for (int m = 0; m < 4; ++m) a[m] = *(const bf16x8*)(cb + offA[m][ks]);
; #pragma unroll
;             for (int n = 0; n < 4; ++n) b[n] = *(const bf16x8*)(cb + offB[n][ks]);
.LBB0_1054:
	v_readfirstlane_b32 s98, v92
	v_readfirstlane_b32 s99, v93
	v_readfirstlane_b32 s6, v94
	v_readfirstlane_b32 s100, v100
	v_readfirstlane_b32 s101, v101
	v_readfirstlane_b32 s10, v149
	s_nop 3
	s_sub_u32 s11, s6, s98
	s_and_b32 s98, s98, 0xffffff80
	s_and_b32 s100, s100, 0xffffff80
	s_nop 1
	v_subrev_u32_e32 v254, s98, v92
	v_subrev_u32_e32 v255, s100, v100
	s_add_i32 s9, s10, 0x8000
	s_mov_b32 m0, s9
	s_nop 0
	global_load_lds_dwordx4 v254, s[98:99]
	s_add_i32 m0, s9, 0x1000
	s_add_u32 s6, s98, s11
	s_addc_u32 s7, s99, 0
	global_load_lds_dwordx4 v254, s[6:7]
	s_add_i32 m0, s9, 0x2000
	s_add_u32 s6, s6, s11
	s_addc_u32 s7, s7, 0
	global_load_lds_dwordx4 v254, s[6:7]
	s_add_i32 m0, s9, 0x3000
	s_add_u32 s6, s6, s11
	s_addc_u32 s7, s7, 0
	global_load_lds_dwordx4 v254, s[6:7]
	s_add_u32 s98, s98, 0x80
	s_addc_u32 s99, s99, 0
	ds_read_b128 v[150:153], v108
	ds_read_b128 v[92:95], v110 offset:16384
	ds_read_b128 v[96:99], v110 offset:16896
	ds_read_b128 v[100:103], v110 offset:20480
	ds_read_b128 v[104:107], v110 offset:20992
	ds_read_b128 v[154:157], v108 offset:2048
	ds_read_b128 v[246:249], v108 offset:4096
	ds_read_b128 v[250:253], v108 offset:6144
	v_readlane_b32 s3, v245, 0
	s_nop 3
	s_bitcmp1_b32 s3, 8
	s_cbranch_scc1 .Lgk_y_1054
	s_setprio 1
	s_branch .Lgk_g_1054

; __device__ __forceinline__ f32x4 mfma16(bf16x8 a, bf16x8 b, f32x4 c) { return __builtin_amdgcn_mfma_f32_16x16x32_bf16(a, b, c, 0, 0, 0); }
; template <class Epi>
; __device__ __forceinline__ void gemm_tile(const bf16_t* __restrict__ A, const bf16_t* __restrict__ Bt, int K, int row0, int col0, const Epi& epi, char* smem,
;                                           bool prefetched, bool nvalid, int nrow0, int ncol0) {
;     ...
;     for (int kt = 0; kt < nk; ++kt) {
;         const int cur = kt & 1;
;         if (kt + 1 < nk) GLDS_STAGE(cur ^ 1, pA, pB, kt + 1);
;         const char* cb = smem + cur * 2 * TILE_B;
; #pragma unroll
;         for (int ks = 0; ks < 2; ++ks) {
;             bf16x8 a[4], b[4];
; #pragma unroll
;             for (int m = 0; m < 4; ++m) a[m] = *(const bf16x8*)(cb + offA[m][ks]);
; #pragma unroll
;             for (int n = 0; n < 4; ++n) b[n] = *(const bf16x8*)(cb + offB[n][ks]);
; #pragma unroll
;             for (int m = 0; m < 4; ++m)
; #pragma unroll
;                 for (int n = 0; n < 4; ++n) acc[m][n] = mfma16(b[n], a[m], acc[m][n]);
;         }
;         asm volatile("s_waitcnt vmcnt(0)" ::: "memory");
;         __syncthreads();
.Lgk_g_1054:
.Lgk_loop_1054:
	s_and_b32 s3, s1, 0x8000
	s_xor_b32 s8, s3, 0x8000
	v_or_b32_e32 v127, s3, v111
	v_add_u32_e32 v144, s3, v109
	s_add_i32 m0, s9, 0x4000
	s_nop 0
	s_waitcnt lgkmcnt(6)
	v_mfma_f32_16x16x32_bf16 v[0:3], v[92:95], v[150:153], v[0:3]
	global_load_lds_dwordx4 v255, s[100:101]
	ds_read_b128 v[128:131], v127 offset:16384
	s_waitcnt lgkmcnt(6)
	v_mfma_f32_16x16x32_bf16 v[4:7], v[96:99], v[150:153], v[4:7]
	ds_read_b128 v[132:135], v127 offset:16896
	s_add_i32 m0, s9, 0x5000
	s_add_u32 s6, s100, s11
	s_addc_u32 s7, s101, 0
	s_waitcnt lgkmcnt(6)
	v_mfma_f32_16x16x32_bf16 v[8:11], v[100:103], v[150:153], v[8:11]
	global_load_lds_dwordx4 v255, s[6:7]
	ds_read_b128 v[136:139], v127 offset:20480
	s_waitcnt lgkmcnt(6)
	v_mfma_f32_16x16x32_bf16 v[12:15], v[104:107], v[150:153], v[12:15]
	ds_read_b128 v[140:143], v127 offset:20992
	ds_read_b128 v[150:153], v144
	s_add_i32 m0, s9, 0x6000
	s_add_u32 s6, s6, s11
	s_addc_u32 s7, s7, 0
	s_waitcnt lgkmcnt(7)
	v_mfma_f32_16x16x32_bf16 v[16:19], v[92:95], v[154:157], v[16:19]
	global_load_lds_dwordx4 v255, s[6:7]
	v_mfma_f32_16x16x32_bf16 v[20:23], v[96:99], v[154:157], v[20:23]
	s_add_i32 m0, s9, 0x7000
	s_add_u32 s6, s6, s11
	s_addc_u32 s7, s7, 0
	v_mfma_f32_16x16x32_bf16 v[24:27], v[100:103], v[154:157], v[24:27]
	global_load_lds_dwordx4 v255, s[6:7]
	s_add_u32 s100, s100, 0x80
	s_addc_u32 s101, s101, 0
	v_mfma_f32_16x16x32_bf16 v[28:31], v[104:107], v[154:157], v[28:31]
	ds_read_b128 v[154:157], v144 offset:2048
	s_waitcnt lgkmcnt(7)
	v_mfma_f32_16x16x32_bf16 v[32:35], v[92:95], v[246:249], v[32:35]
	v_mfma_f32_16x16x32_bf16 v[36:39], v[96:99], v[246:249], v[36:39]
	v_mfma_f32_16x16x32_bf16 v[40:43], v[100:103], v[246:249], v[40:43]
	v_mfma_f32_16x16x32_bf16 v[44:47], v[104:107], v[246:249], v[44:47]
	ds_read_b128 v[246:249], v144 offset:4096
	s_waitcnt lgkmcnt(7)
	v_mfma_f32_16x16x32_bf16 v[48:51], v[92:95], v[250:253], v[48:51]
	v_mfma_f32_16x16x32_bf16 v[52:55], v[96:99], v[250:253], v[52:55]
	v_mfma_f32_16x16x32_bf16 v[56:59], v[100:103], v[250:253], v[56:59]
	v_mfma_f32_16x16x32_bf16 v[60:63], v[104:107], v[250:253], v[60:63]
	ds_read_b128 v[250:253], v144 offset:6144
	s_waitcnt lgkmcnt(3)
	v_mfma_f32_16x16x32_bf16 v[0:3], v[128:131], v[150:153], v[0:3]
	v_mfma_f32_16x16x32_bf16 v[4:7], v[132:135], v[150:153], v[4:7]
	v_mfma_f32_16x16x32_bf16 v[8:11], v[136:139], v[150:153], v[8:11]
	v_mfma_f32_16x16x32_bf16 v[12:15], v[140:143], v[150:153], v[12:15]
	s_waitcnt lgkmcnt(2)
	v_mfma_f32_16x16x32_bf16 v[16:19], v[128:131], v[154:157], v[16:19]
	v_mfma_f32_16x16x32_bf16 v[20:23], v[132:135], v[154:157], v[20:23]
	v_mfma_f32_16x16x32_bf16 v[24:27], v[136:139], v[154:157], v[24:27]
	v_mfma_f32_16x16x32_bf16 v[28:31], v[140:143], v[154:157], v[28:31]
	s_waitcnt vmcnt(0)
	s_waitcnt lgkmcnt(0)
	s_barrier
	s_add_i32 s1, s1, 0x8000
	s_cmp_eq_u32 s1, 0x1f8000
	s_cbranch_scc1 .Lgk_tail_1054
	v_or_b32_e32 v127, s8, v110
	v_add_u32_e32 v144, s8, v108
	s_add_i32 s9, s3, s10
	ds_read_b128 v[150:153], v144
	ds_read_b128 v[92:95], v127 offset:16384
	s_mov_b32 m0, s9
	s_nop 0
	v_mfma_f32_16x16x32_bf16 v[32:35], v[128:131], v[246:249], v[32:35]
	global_load_lds_dwordx4 v254, s[98:99]
	ds_read_b128 v[96:99], v127 offset:16896
	v_mfma_f32_16x16x32_bf16 v[36:39], v[132:135], v[246:249], v[36:39]
	ds_read_b128 v[100:103], v127 offset:20480
	s_add_i32 m0, s9, 0x1000
	s_add_u32 s6, s98, s11
	s_addc_u32 s7, s99, 0
	v_mfma_f32_16x16x32_bf16 v[40:43], v[136:139], v[246:249], v[40:43]
	global_load_lds_dwordx4 v254, s[6:7]
	ds_read_b128 v[104:107], v127 offset:20992
	v_mfma_f32_16x16x32_bf16 v[44:47], v[140:143], v[246:249], v[44:47]
	ds_read_b128 v[154:157], v144 offset:2048
	ds_read_b128 v[246:249], v144 offset:4096
	s_add_i32 m0, s9, 0x2000
	s_add_u32 s6, s6, s11
	s_addc_u32 s7, s7, 0
	v_mfma_f32_16x16x32_bf16 v[48:51], v[128:131], v[250:253], v[48:51]
	global_load_lds_dwordx4 v254, s[6:7]
	v_mfma_f32_16x16x32_bf16 v[52:55], v[132:135], v[250:253], v[52:55]
	s_add_i32 m0, s9, 0x3000
	s_add_u32 s6, s6, s11
	s_addc_u32 s7, s7, 0
	v_mfma_f32_16x16x32_bf16 v[56:59], v[136:139], v[250:253], v[56:59]
	global_load_lds_dwordx4 v254, s[6:7]
	s_add_u32 s98, s98, 0x80
	s_addc_u32 s99, s99, 0
	v_mfma_f32_16x16x32_bf16 v[60:63], v[140:143], v[250:253], v[60:63]
	ds_read_b128 v[250:253], v144 offset:6144
	s_branch .Lgk_loop_1054
